# attention QK^T K-fragment LDS reads pipelined through a 12-quad ring with counted lgkmcnt; first o-accumulator copy skipped on the compute path; EpiQKV SSQ loads prefetched 4 rows ahead
# speedup vs baseline: 1.0175x; 1.0092x over previous
; __device__ __forceinline__ void attn_unit(LAS unsigned char* lds, const bf16_t* __restrict__ Q, const bf16_t* __restrict__ Kg, const bf16_t* __restrict__ Vg, bf16_t* __restrict__ AO, int b, int h, int qb) {
;     ...
;     for (int t = 0; t < NT; ++t) {
;         const int kb = t * KVBLK;
;         if (t + 2 < NT) { if (bi == 0) ATT_LOAD(t + 2, 2); else if (bi == 1) ATT_LOAD(t + 2, 0); else ATT_LOAD(t + 2, 1); }
;         if (bi == 0) ATT_STEP(0); else if (bi == 1) ATT_STEP(1); else ATT_STEP(2);
.LBB0_313:
	s_sub_i32 s0, s76, 63
	s_cmp_le_i32 s0, s82
	s_cselect_b64 s[42:43], -1, 0
	s_mov_b64 s[26:27], -1
	s_mov_b64 s[48:49], 0
	s_cmp_lt_i32 s96, 1
	s_mov_b64 s[0:1], 0
	s_cbranch_scc1 .LBB0_337
	s_cmp_eq_u32 s96, 1
	s_mov_b64 s[0:1], -1
	s_cbranch_scc0 .LBB0_324
	s_andn2_b64 vcc, exec, s[42:43]
	s_cbranch_vccz .Latt_c1_compute
	v_mov_b64_e32 v[78:79], v[62:63]
	v_mov_b64_e32 v[94:95], v[46:47]
	v_mov_b64_e32 v[110:111], v[30:31]
	v_mov_b64_e32 v[126:127], v[14:15]
	v_mov_b32_e32 v251, v249
	v_mov_b32_e32 v128, v250
	v_mov_b64_e32 v[76:77], v[60:61]
	v_mov_b64_e32 v[74:75], v[58:59]
	v_mov_b64_e32 v[72:73], v[56:57]
	v_mov_b64_e32 v[70:71], v[54:55]
	v_mov_b64_e32 v[68:69], v[52:53]
	v_mov_b64_e32 v[66:67], v[50:51]
	v_mov_b64_e32 v[64:65], v[48:49]
	v_mov_b64_e32 v[92:93], v[44:45]
	v_mov_b64_e32 v[90:91], v[42:43]
	v_mov_b64_e32 v[88:89], v[40:41]
	v_mov_b64_e32 v[86:87], v[38:39]
	v_mov_b64_e32 v[84:85], v[36:37]
	v_mov_b64_e32 v[82:83], v[34:35]
	v_mov_b64_e32 v[80:81], v[32:33]
	v_mov_b64_e32 v[108:109], v[28:29]
	v_mov_b64_e32 v[106:107], v[26:27]
	v_mov_b64_e32 v[104:105], v[24:25]
	v_mov_b64_e32 v[102:103], v[22:23]
	v_mov_b64_e32 v[100:101], v[20:21]
	v_mov_b64_e32 v[98:99], v[18:19]
	v_mov_b64_e32 v[96:97], v[16:17]
	v_mov_b64_e32 v[124:125], v[12:13]
	v_mov_b64_e32 v[122:123], v[10:11]
	v_mov_b64_e32 v[120:121], v[8:9]
	v_mov_b64_e32 v[118:119], v[6:7]
	v_mov_b64_e32 v[116:117], v[4:5]
	v_mov_b64_e32 v[114:115], v[2:3]
	v_mov_b64_e32 v[112:113], v[0:1]
	s_branch .LBB0_323
; #define LAS __attribute__((address_space(3)))
; template <int KB>
; __device__ __forceinline__ void qkt(f32x16& p0, f32x16& p1, const LAS char* K_lds, int r32, int hi, const bf16x8* qr) {
;     p0 = f32x16{}; p1 = f32x16{};
;     const LAS char* kb[4];
; #pragma unroll
;     for (int dd = 0; dd < 4; ++dd) kb[dd] = K_lds + KB * SHM_K + r32 * 384 + (((2 * dd + hi) ^ (r32 & 7)) << 4);
; #pragma unroll
;     for (int d0 = 0; d0 < 12; ++d0) { const LAS char* a = kb[d0 & 3] + (d0 >> 2) * 128;
;         bf16x8 b0 = *(const LAS bf16x8*)(a);
;         bf16x8 b1 = *(const LAS bf16x8*)(a + 32 * 384);
;         p0 = __builtin_amdgcn_mfma_f32_32x32x16_bf16(b0, qr[d0], p0, 0, 0, 0);
;         p1 = __builtin_amdgcn_mfma_f32_32x32x16_bf16(b1, qr[d0], p1, 0, 0, 0); }
; }
.Latt_c1_compute:
	v_add_u32_e32 v68, v240, v241
	v_add_u32_e32 v69, v240, v243
	v_add_u32_e32 v70, v240, v244
	v_add_u32_e32 v71, v240, v245
	s_cmp_le_i32 s76, s31
	ds_read_b128 v[72:75], v68
	ds_read_b128 v[76:79], v68 offset:12288
	ds_read_b128 v[80:83], v69
	ds_read_b128 v[84:87], v69 offset:12288
	ds_read_b128 v[88:91], v70
	ds_read_b128 v[92:95], v70 offset:12288
	ds_read_b128 v[96:99], v71
	ds_read_b128 v[100:103], v71 offset:12288
	ds_read_b128 v[104:107], v68 offset:128
	ds_read_b128 v[108:111], v68 offset:12416
	ds_read_b128 v[112:115], v69 offset:128
	ds_read_b128 v[116:119], v69 offset:12416
	s_waitcnt lgkmcnt(11)
	v_mfma_f32_32x32x16_bf16 v[144:159], v[72:75], v[160:163], 0
	ds_read_b128 v[72:75], v70 offset:128
	s_waitcnt lgkmcnt(11)
	v_mfma_f32_32x32x16_bf16 v[128:143], v[76:79], v[160:163], 0
	ds_read_b128 v[76:79], v70 offset:12416
	s_waitcnt lgkmcnt(11)
	v_mfma_f32_32x32x16_bf16 v[144:159], v[80:83], v[164:167], v[144:159]
	ds_read_b128 v[80:83], v71 offset:128
	s_waitcnt lgkmcnt(11)
	v_mfma_f32_32x32x16_bf16 v[128:143], v[84:87], v[164:167], v[128:143]
	ds_read_b128 v[84:87], v71 offset:12416
	s_waitcnt lgkmcnt(11)
	v_mfma_f32_32x32x16_bf16 v[144:159], v[88:91], v[168:171], v[144:159]
	ds_read_b128 v[88:91], v68 offset:256
	s_waitcnt lgkmcnt(11)
	v_mfma_f32_32x32x16_bf16 v[128:143], v[92:95], v[168:171], v[128:143]
	ds_read_b128 v[92:95], v68 offset:12544
	s_waitcnt lgkmcnt(11)
	v_mfma_f32_32x32x16_bf16 v[144:159], v[96:99], v[172:175], v[144:159]
	ds_read_b128 v[96:99], v69 offset:256
	s_waitcnt lgkmcnt(11)
	v_mfma_f32_32x32x16_bf16 v[128:143], v[100:103], v[172:175], v[128:143]
	ds_read_b128 v[100:103], v69 offset:12544
	s_waitcnt lgkmcnt(11)
	v_mfma_f32_32x32x16_bf16 v[144:159], v[104:107], v[176:179], v[144:159]
	ds_read_b128 v[104:107], v70 offset:256
	s_waitcnt lgkmcnt(11)
	v_mfma_f32_32x32x16_bf16 v[128:143], v[108:111], v[176:179], v[128:143]
	ds_read_b128 v[108:111], v70 offset:12544
	s_waitcnt lgkmcnt(11)
	v_mfma_f32_32x32x16_bf16 v[144:159], v[112:115], v[180:183], v[144:159]
	ds_read_b128 v[112:115], v71 offset:256
	s_waitcnt lgkmcnt(11)
	v_mfma_f32_32x32x16_bf16 v[128:143], v[116:119], v[180:183], v[128:143]
	ds_read_b128 v[116:119], v71 offset:12544
	s_waitcnt lgkmcnt(11)
	v_mfma_f32_32x32x16_bf16 v[144:159], v[72:75], v[184:187], v[144:159]
	s_waitcnt lgkmcnt(10)
	v_mfma_f32_32x32x16_bf16 v[128:143], v[76:79], v[184:187], v[128:143]
	s_waitcnt lgkmcnt(9)
	v_mfma_f32_32x32x16_bf16 v[144:159], v[80:83], v[188:191], v[144:159]
	s_waitcnt lgkmcnt(8)
	v_mfma_f32_32x32x16_bf16 v[128:143], v[84:87], v[188:191], v[128:143]
	s_waitcnt lgkmcnt(7)
	v_mfma_f32_32x32x16_bf16 v[144:159], v[88:91], v[192:195], v[144:159]
	s_waitcnt lgkmcnt(6)
	v_mfma_f32_32x32x16_bf16 v[128:143], v[92:95], v[192:195], v[128:143]
	s_waitcnt lgkmcnt(5)
	v_mfma_f32_32x32x16_bf16 v[144:159], v[96:99], v[196:199], v[144:159]
	s_waitcnt lgkmcnt(4)
	v_mfma_f32_32x32x16_bf16 v[128:143], v[100:103], v[196:199], v[128:143]
	s_waitcnt lgkmcnt(3)
	v_mfma_f32_32x32x16_bf16 v[144:159], v[104:107], v[200:203], v[144:159]
	s_waitcnt lgkmcnt(2)
	v_mfma_f32_32x32x16_bf16 v[128:143], v[108:111], v[200:203], v[128:143]
	s_waitcnt lgkmcnt(1)
	v_mfma_f32_32x32x16_bf16 v[144:159], v[112:115], v[204:207], v[144:159]
	s_waitcnt lgkmcnt(0)
	v_mfma_f32_32x32x16_bf16 v[128:143], v[116:119], v[204:207], v[128:143]
	s_cbranch_scc1 .LBB0_318
	v_add_u32_e32 v64, 27, v248
	v_cmp_lt_i32_e32 vcc, -1, v64
	s_nop 5
	v_cndmask_b32_e32 v144, v225, v144, vcc
	v_cmp_lt_i32_e32 vcc, 31, v64
	v_add_u32_e32 v64, 26, v248
	s_nop 0
	v_cndmask_b32_e32 v128, v225, v128, vcc
	v_cmp_lt_i32_e32 vcc, -1, v64
	s_nop 1
	v_cndmask_b32_e32 v145, v225, v145, vcc
	v_cmp_lt_i32_e32 vcc, 31, v64
	v_add_u32_e32 v64, 25, v248
	s_nop 0
	v_cndmask_b32_e32 v129, v225, v129, vcc
	v_cmp_lt_i32_e32 vcc, -1, v64
	s_nop 1
	v_cndmask_b32_e32 v146, v225, v146, vcc
	v_cmp_lt_i32_e32 vcc, 31, v64
	v_add_u32_e32 v64, 24, v248
	s_nop 0
	v_cndmask_b32_e32 v130, v225, v130, vcc
	v_cmp_lt_i32_e32 vcc, -1, v64
	s_nop 1
	v_cndmask_b32_e32 v147, v225, v147, vcc
	v_cmp_lt_i32_e32 vcc, 31, v64
	v_add_u32_e32 v64, 19, v248
	s_nop 0
	v_cndmask_b32_e32 v131, v225, v131, vcc
	v_cmp_lt_i32_e32 vcc, -1, v64
	s_nop 1
	v_cndmask_b32_e32 v148, v225, v148, vcc
	v_cmp_lt_i32_e32 vcc, 31, v64
	v_add_u32_e32 v64, 18, v248
	s_nop 0
	v_cndmask_b32_e32 v132, v225, v132, vcc
	v_cmp_lt_i32_e32 vcc, -1, v64
	s_nop 1
	v_cndmask_b32_e32 v149, v225, v149, vcc
	v_cmp_lt_i32_e32 vcc, 31, v64
	v_add_u32_e32 v64, 17, v248
	s_nop 0
	v_cndmask_b32_e32 v133, v225, v133, vcc
	v_cmp_lt_i32_e32 vcc, -1, v64
	s_nop 1
	v_cndmask_b32_e32 v150, v225, v150, vcc
	v_cmp_lt_i32_e32 vcc, 31, v64
	v_add_u32_e32 v64, 16, v248
	s_nop 0
	v_cndmask_b32_e32 v134, v225, v134, vcc
	v_cmp_lt_i32_e32 vcc, -1, v64
	s_nop 1
	v_cndmask_b32_e32 v151, v225, v151, vcc
	v_cmp_lt_i32_e32 vcc, 31, v64
	v_add_u32_e32 v64, 11, v248
	s_nop 0
	v_cndmask_b32_e32 v135, v225, v135, vcc
	v_cmp_lt_i32_e32 vcc, -1, v64
	s_nop 1
	v_cndmask_b32_e32 v152, v225, v152, vcc
	v_cmp_lt_i32_e32 vcc, 31, v64
	v_add_u32_e32 v64, 10, v248
	s_nop 0
	v_cndmask_b32_e32 v136, v225, v136, vcc
	v_cmp_lt_i32_e32 vcc, -1, v64
	s_nop 1
	v_cndmask_b32_e32 v153, v225, v153, vcc
	v_cmp_lt_i32_e32 vcc, 31, v64
	v_add_u32_e32 v64, 9, v248
	s_nop 0
	v_cndmask_b32_e32 v137, v225, v137, vcc
	v_cmp_lt_i32_e32 vcc, -1, v64
	s_nop 1
	v_cndmask_b32_e32 v154, v225, v154, vcc
	v_cmp_lt_i32_e32 vcc, 31, v64
	v_add_u32_e32 v64, 8, v248
	s_nop 0
	v_cndmask_b32_e32 v138, v225, v138, vcc
	v_cmp_lt_i32_e32 vcc, -1, v64
	s_nop 1
	v_cndmask_b32_e32 v155, v225, v155, vcc
	v_cmp_lt_i32_e32 vcc, 31, v64
	v_add_u32_e32 v64, 3, v248
	s_nop 0
	v_cndmask_b32_e32 v139, v225, v139, vcc
	v_cmp_lt_i32_e32 vcc, -1, v64
	s_nop 1
	v_cndmask_b32_e32 v156, v225, v156, vcc
	v_cmp_lt_i32_e32 vcc, 31, v64
	v_add_u32_e32 v64, 2, v248
	s_nop 0
	v_cndmask_b32_e32 v140, v225, v140, vcc
	v_cmp_lt_i32_e32 vcc, -1, v64
	s_nop 1
	v_cndmask_b32_e32 v157, v225, v157, vcc
	v_cmp_lt_i32_e32 vcc, 31, v64
	v_add_u32_e32 v64, 1, v248
	s_nop 0
	v_cndmask_b32_e32 v141, v225, v141, vcc
	v_cmp_lt_i32_e32 vcc, -1, v64
	s_nop 1
	v_cndmask_b32_e32 v158, v225, v158, vcc
	v_cmp_lt_i32_e32 vcc, 31, v64
	s_nop 1
	v_cndmask_b32_e32 v142, v225, v142, vcc
	v_cmp_lt_i32_e32 vcc, -1, v248
	s_nop 1
	v_cndmask_b32_e32 v159, v225, v159, vcc
	v_cmp_lt_i32_e32 vcc, 31, v248
	s_nop 1
	v_cndmask_b32_e32 v143, v225, v143, vcc

.LBB0_326:
	s_nop 7
	s_and_b64 vcc, exec, s[42:43]
	s_cbranch_vccz .Latt_c2_compute
	v_mov_b64_e32 v[78:79], v[62:63]
	v_mov_b64_e32 v[94:95], v[46:47]
	v_mov_b64_e32 v[110:111], v[30:31]
	v_mov_b64_e32 v[126:127], v[14:15]
	v_mov_b32_e32 v251, v249
	v_mov_b32_e32 v128, v250
	v_mov_b64_e32 v[76:77], v[60:61]
	v_mov_b64_e32 v[74:75], v[58:59]
	v_mov_b64_e32 v[72:73], v[56:57]
	v_mov_b64_e32 v[70:71], v[54:55]
	v_mov_b64_e32 v[68:69], v[52:53]
	v_mov_b64_e32 v[66:67], v[50:51]
	v_mov_b64_e32 v[64:65], v[48:49]
	v_mov_b64_e32 v[92:93], v[44:45]
	v_mov_b64_e32 v[90:91], v[42:43]
	v_mov_b64_e32 v[88:89], v[40:41]
	v_mov_b64_e32 v[86:87], v[38:39]
	v_mov_b64_e32 v[84:85], v[36:37]
	v_mov_b64_e32 v[82:83], v[34:35]
	v_mov_b64_e32 v[80:81], v[32:33]
	v_mov_b64_e32 v[108:109], v[28:29]
	v_mov_b64_e32 v[106:107], v[26:27]
	v_mov_b64_e32 v[104:105], v[24:25]
	v_mov_b64_e32 v[102:103], v[22:23]
	v_mov_b64_e32 v[100:101], v[20:21]
	v_mov_b64_e32 v[98:99], v[18:19]
	v_mov_b64_e32 v[96:97], v[16:17]
	v_mov_b64_e32 v[124:125], v[12:13]
	v_mov_b64_e32 v[122:123], v[10:11]
	v_mov_b64_e32 v[120:121], v[8:9]
	v_mov_b64_e32 v[118:119], v[6:7]
	v_mov_b64_e32 v[116:117], v[4:5]
	v_mov_b64_e32 v[114:115], v[2:3]
	v_mov_b64_e32 v[112:113], v[0:1]
	s_branch .LBB0_334
; #define LAS __attribute__((address_space(3)))
; template <int KB>
; __device__ __forceinline__ void qkt(f32x16& p0, f32x16& p1, const LAS char* K_lds, int r32, int hi, const bf16x8* qr) {
;     p0 = f32x16{}; p1 = f32x16{};
;     const LAS char* kb[4];
; #pragma unroll
;     for (int dd = 0; dd < 4; ++dd) kb[dd] = K_lds + KB * SHM_K + r32 * 384 + (((2 * dd + hi) ^ (r32 & 7)) << 4);
; #pragma unroll
;     for (int d0 = 0; d0 < 12; ++d0) { const LAS char* a = kb[d0 & 3] + (d0 >> 2) * 128;
;         bf16x8 b0 = *(const LAS bf16x8*)(a);
;         bf16x8 b1 = *(const LAS bf16x8*)(a + 32 * 384);
;         p0 = __builtin_amdgcn_mfma_f32_32x32x16_bf16(b0, qr[d0], p0, 0, 0, 0);
;         p1 = __builtin_amdgcn_mfma_f32_32x32x16_bf16(b1, qr[d0], p1, 0, 0, 0); }
; }
.Latt_c2_compute:
	v_add_u32_e32 v68, v247, v241
	v_add_u32_e32 v69, v247, v243
	v_add_u32_e32 v70, v247, v244
	v_add_u32_e32 v71, v247, v245
	s_cmp_le_i32 s76, s31
	ds_read_b128 v[72:75], v68
	ds_read_b128 v[76:79], v68 offset:12288
	ds_read_b128 v[80:83], v69
	ds_read_b128 v[84:87], v69 offset:12288
	ds_read_b128 v[88:91], v70
	ds_read_b128 v[92:95], v70 offset:12288
	ds_read_b128 v[96:99], v71
	ds_read_b128 v[100:103], v71 offset:12288
	ds_read_b128 v[104:107], v68 offset:128
	ds_read_b128 v[108:111], v68 offset:12416
	ds_read_b128 v[112:115], v69 offset:128
	ds_read_b128 v[116:119], v69 offset:12416
	s_waitcnt lgkmcnt(11)
	v_mfma_f32_32x32x16_bf16 v[144:159], v[72:75], v[160:163], 0
	ds_read_b128 v[72:75], v70 offset:128
	s_waitcnt lgkmcnt(11)
	v_mfma_f32_32x32x16_bf16 v[128:143], v[76:79], v[160:163], 0
	ds_read_b128 v[76:79], v70 offset:12416
	s_waitcnt lgkmcnt(11)
	v_mfma_f32_32x32x16_bf16 v[144:159], v[80:83], v[164:167], v[144:159]
	ds_read_b128 v[80:83], v71 offset:128
	s_waitcnt lgkmcnt(11)
	v_mfma_f32_32x32x16_bf16 v[128:143], v[84:87], v[164:167], v[128:143]
	ds_read_b128 v[84:87], v71 offset:12416
	s_waitcnt lgkmcnt(11)
	v_mfma_f32_32x32x16_bf16 v[144:159], v[88:91], v[168:171], v[144:159]
	ds_read_b128 v[88:91], v68 offset:256
	s_waitcnt lgkmcnt(11)
	v_mfma_f32_32x32x16_bf16 v[128:143], v[92:95], v[168:171], v[128:143]
	ds_read_b128 v[92:95], v68 offset:12544
	s_waitcnt lgkmcnt(11)
	v_mfma_f32_32x32x16_bf16 v[144:159], v[96:99], v[172:175], v[144:159]
	ds_read_b128 v[96:99], v69 offset:256
	s_waitcnt lgkmcnt(11)
	v_mfma_f32_32x32x16_bf16 v[128:143], v[100:103], v[172:175], v[128:143]
	ds_read_b128 v[100:103], v69 offset:12544
	s_waitcnt lgkmcnt(11)
	v_mfma_f32_32x32x16_bf16 v[144:159], v[104:107], v[176:179], v[144:159]
	ds_read_b128 v[104:107], v70 offset:256
	s_waitcnt lgkmcnt(11)
	v_mfma_f32_32x32x16_bf16 v[128:143], v[108:111], v[176:179], v[128:143]
	ds_read_b128 v[108:111], v70 offset:12544
	s_waitcnt lgkmcnt(11)
	v_mfma_f32_32x32x16_bf16 v[144:159], v[112:115], v[180:183], v[144:159]
	ds_read_b128 v[112:115], v71 offset:256
	s_waitcnt lgkmcnt(11)
	v_mfma_f32_32x32x16_bf16 v[128:143], v[116:119], v[180:183], v[128:143]
	ds_read_b128 v[116:119], v71 offset:12544
	s_waitcnt lgkmcnt(11)
	v_mfma_f32_32x32x16_bf16 v[144:159], v[72:75], v[184:187], v[144:159]
	s_waitcnt lgkmcnt(10)
	v_mfma_f32_32x32x16_bf16 v[128:143], v[76:79], v[184:187], v[128:143]
	s_waitcnt lgkmcnt(9)
	v_mfma_f32_32x32x16_bf16 v[144:159], v[80:83], v[188:191], v[144:159]
	s_waitcnt lgkmcnt(8)
	v_mfma_f32_32x32x16_bf16 v[128:143], v[84:87], v[188:191], v[128:143]
	s_waitcnt lgkmcnt(7)
	v_mfma_f32_32x32x16_bf16 v[144:159], v[88:91], v[192:195], v[144:159]
	s_waitcnt lgkmcnt(6)
	v_mfma_f32_32x32x16_bf16 v[128:143], v[92:95], v[192:195], v[128:143]
	s_waitcnt lgkmcnt(5)
	v_mfma_f32_32x32x16_bf16 v[144:159], v[96:99], v[196:199], v[144:159]
	s_waitcnt lgkmcnt(4)
	v_mfma_f32_32x32x16_bf16 v[128:143], v[100:103], v[196:199], v[128:143]
	s_waitcnt lgkmcnt(3)
	v_mfma_f32_32x32x16_bf16 v[144:159], v[104:107], v[200:203], v[144:159]
	s_waitcnt lgkmcnt(2)
	v_mfma_f32_32x32x16_bf16 v[128:143], v[108:111], v[200:203], v[128:143]
	s_waitcnt lgkmcnt(1)
	v_mfma_f32_32x32x16_bf16 v[144:159], v[112:115], v[204:207], v[144:159]
	s_waitcnt lgkmcnt(0)
	v_mfma_f32_32x32x16_bf16 v[128:143], v[116:119], v[204:207], v[128:143]
	s_cbranch_scc1 .LBB0_329
	v_add_u32_e32 v64, 27, v248
	v_cmp_lt_i32_e32 vcc, -1, v64
	s_nop 5
	v_cndmask_b32_e32 v144, v225, v144, vcc
	v_cmp_lt_i32_e32 vcc, 31, v64
	v_add_u32_e32 v64, 26, v248
	s_nop 0
	v_cndmask_b32_e32 v128, v225, v128, vcc
	v_cmp_lt_i32_e32 vcc, -1, v64
	s_nop 1
	v_cndmask_b32_e32 v145, v225, v145, vcc
	v_cmp_lt_i32_e32 vcc, 31, v64
	v_add_u32_e32 v64, 25, v248
	s_nop 0
	v_cndmask_b32_e32 v129, v225, v129, vcc
	v_cmp_lt_i32_e32 vcc, -1, v64
	s_nop 1
	v_cndmask_b32_e32 v146, v225, v146, vcc
	v_cmp_lt_i32_e32 vcc, 31, v64
	v_add_u32_e32 v64, 24, v248
	s_nop 0
	v_cndmask_b32_e32 v130, v225, v130, vcc
	v_cmp_lt_i32_e32 vcc, -1, v64
	s_nop 1
	v_cndmask_b32_e32 v147, v225, v147, vcc
	v_cmp_lt_i32_e32 vcc, 31, v64
	v_add_u32_e32 v64, 19, v248
	s_nop 0
	v_cndmask_b32_e32 v131, v225, v131, vcc
	v_cmp_lt_i32_e32 vcc, -1, v64
	s_nop 1
	v_cndmask_b32_e32 v148, v225, v148, vcc
	v_cmp_lt_i32_e32 vcc, 31, v64
	v_add_u32_e32 v64, 18, v248
	s_nop 0
	v_cndmask_b32_e32 v132, v225, v132, vcc
	v_cmp_lt_i32_e32 vcc, -1, v64
	s_nop 1
	v_cndmask_b32_e32 v149, v225, v149, vcc
	v_cmp_lt_i32_e32 vcc, 31, v64
	v_add_u32_e32 v64, 17, v248
	s_nop 0
	v_cndmask_b32_e32 v133, v225, v133, vcc
	v_cmp_lt_i32_e32 vcc, -1, v64
	s_nop 1
	v_cndmask_b32_e32 v150, v225, v150, vcc
	v_cmp_lt_i32_e32 vcc, 31, v64
	v_add_u32_e32 v64, 16, v248
	s_nop 0
	v_cndmask_b32_e32 v134, v225, v134, vcc
	v_cmp_lt_i32_e32 vcc, -1, v64
	s_nop 1
	v_cndmask_b32_e32 v151, v225, v151, vcc
	v_cmp_lt_i32_e32 vcc, 31, v64
	v_add_u32_e32 v64, 11, v248
	s_nop 0
	v_cndmask_b32_e32 v135, v225, v135, vcc
	v_cmp_lt_i32_e32 vcc, -1, v64
	s_nop 1
	v_cndmask_b32_e32 v152, v225, v152, vcc
	v_cmp_lt_i32_e32 vcc, 31, v64
	v_add_u32_e32 v64, 10, v248
	s_nop 0
	v_cndmask_b32_e32 v136, v225, v136, vcc
	v_cmp_lt_i32_e32 vcc, -1, v64
	s_nop 1
	v_cndmask_b32_e32 v153, v225, v153, vcc
	v_cmp_lt_i32_e32 vcc, 31, v64
	v_add_u32_e32 v64, 9, v248
	s_nop 0
	v_cndmask_b32_e32 v137, v225, v137, vcc
	v_cmp_lt_i32_e32 vcc, -1, v64
	s_nop 1
	v_cndmask_b32_e32 v154, v225, v154, vcc
	v_cmp_lt_i32_e32 vcc, 31, v64
	v_add_u32_e32 v64, 8, v248
	s_nop 0
	v_cndmask_b32_e32 v138, v225, v138, vcc
	v_cmp_lt_i32_e32 vcc, -1, v64
	s_nop 1
	v_cndmask_b32_e32 v155, v225, v155, vcc
	v_cmp_lt_i32_e32 vcc, 31, v64
	v_add_u32_e32 v64, 3, v248
	s_nop 0
	v_cndmask_b32_e32 v139, v225, v139, vcc
	v_cmp_lt_i32_e32 vcc, -1, v64
	s_nop 1
	v_cndmask_b32_e32 v156, v225, v156, vcc
	v_cmp_lt_i32_e32 vcc, 31, v64
	v_add_u32_e32 v64, 2, v248
	s_nop 0
	v_cndmask_b32_e32 v140, v225, v140, vcc
	v_cmp_lt_i32_e32 vcc, -1, v64
	s_nop 1
	v_cndmask_b32_e32 v157, v225, v157, vcc
	v_cmp_lt_i32_e32 vcc, 31, v64
	v_add_u32_e32 v64, 1, v248
	s_nop 0
	v_cndmask_b32_e32 v141, v225, v141, vcc
	v_cmp_lt_i32_e32 vcc, -1, v64
	s_nop 1
	v_cndmask_b32_e32 v158, v225, v158, vcc
	v_cmp_lt_i32_e32 vcc, 31, v64
	s_nop 1
	v_cndmask_b32_e32 v142, v225, v142, vcc
	v_cmp_lt_i32_e32 vcc, -1, v248
	s_nop 1
	v_cndmask_b32_e32 v159, v225, v159, vcc
	v_cmp_lt_i32_e32 vcc, 31, v248
	s_nop 1
	v_cndmask_b32_e32 v143, v225, v143, vcc

; #define LAS __attribute__((address_space(3)))
; template <int KB>
; __device__ __forceinline__ void qkt(f32x16& p0, f32x16& p1, const LAS char* K_lds, int r32, int hi, const bf16x8* qr) {
;     p0 = f32x16{}; p1 = f32x16{};
;     const LAS char* kb[4];
; #pragma unroll
;     for (int dd = 0; dd < 4; ++dd) kb[dd] = K_lds + KB * SHM_K + r32 * 384 + (((2 * dd + hi) ^ (r32 & 7)) << 4);
; #pragma unroll
;     for (int d0 = 0; d0 < 12; ++d0) { const LAS char* a = kb[d0 & 3] + (d0 >> 2) * 128;
;         bf16x8 b0 = *(const LAS bf16x8*)(a);
;         bf16x8 b1 = *(const LAS bf16x8*)(a + 32 * 384);
;         p0 = __builtin_amdgcn_mfma_f32_32x32x16_bf16(b0, qr[d0], p0, 0, 0, 0);
;         p1 = __builtin_amdgcn_mfma_f32_32x32x16_bf16(b1, qr[d0], p1, 0, 0, 0); }
; }
.LBB0_340:
	s_and_b64 vcc, exec, s[42:43]
	s_cbranch_vccnz .LBB0_348
	s_nop 4
	v_add_u32_e32 v100, v246, v241
	v_add_u32_e32 v101, v246, v243
	v_add_u32_e32 v102, v246, v244
	v_add_u32_e32 v103, v246, v245
	s_cmp_le_i32 s76, s31
	ds_read_b128 v[96:99], v100 offset:49152
	ds_read_b128 v[104:107], v100 offset:61440
	ds_read_b128 v[108:111], v101 offset:49152
	ds_read_b128 v[112:115], v101 offset:61440
	ds_read_b128 v[116:119], v102 offset:49152
	ds_read_b128 v[120:123], v102 offset:61440
	ds_read_b128 v[124:127], v103 offset:49152
	s_waitcnt lgkmcnt(6)
	v_mfma_f32_32x32x16_bf16 v[80:95], v[96:99], v[160:163], 0
	ds_read_b128 v[96:99], v103 offset:61440
	s_waitcnt lgkmcnt(6)
	v_mfma_f32_32x32x16_bf16 v[64:79], v[104:107], v[160:163], 0
	ds_read_b128 v[104:107], v100 offset:49280
	s_waitcnt lgkmcnt(6)
	v_mfma_f32_32x32x16_bf16 v[80:95], v[108:111], v[164:167], v[80:95]
	ds_read_b128 v[108:111], v100 offset:61568
	s_waitcnt lgkmcnt(6)
	v_mfma_f32_32x32x16_bf16 v[64:79], v[112:115], v[164:167], v[64:79]
	ds_read_b128 v[112:115], v101 offset:49280
	s_waitcnt lgkmcnt(6)
	v_mfma_f32_32x32x16_bf16 v[80:95], v[116:119], v[168:171], v[80:95]
	ds_read_b128 v[116:119], v101 offset:61568
	s_waitcnt lgkmcnt(6)
	v_mfma_f32_32x32x16_bf16 v[64:79], v[120:123], v[168:171], v[64:79]
	ds_read_b128 v[120:123], v102 offset:49280
	s_waitcnt lgkmcnt(6)
	v_mfma_f32_32x32x16_bf16 v[80:95], v[124:127], v[172:175], v[80:95]
	ds_read_b128 v[124:127], v102 offset:61568
	s_waitcnt lgkmcnt(6)
	v_mfma_f32_32x32x16_bf16 v[64:79], v[96:99], v[172:175], v[64:79]
	ds_read_b128 v[96:99], v103 offset:49280
	s_waitcnt lgkmcnt(6)
	v_mfma_f32_32x32x16_bf16 v[80:95], v[104:107], v[176:179], v[80:95]
	ds_read_b128 v[104:107], v103 offset:61568
	s_waitcnt lgkmcnt(6)
	v_mfma_f32_32x32x16_bf16 v[64:79], v[108:111], v[176:179], v[64:79]
	ds_read_b128 v[108:111], v100 offset:49408
	s_waitcnt lgkmcnt(6)
	v_mfma_f32_32x32x16_bf16 v[80:95], v[112:115], v[180:183], v[80:95]
	ds_read_b128 v[112:115], v100 offset:61696
	s_waitcnt lgkmcnt(6)
	v_mfma_f32_32x32x16_bf16 v[64:79], v[116:119], v[180:183], v[64:79]
	ds_read_b128 v[116:119], v101 offset:49408
	s_waitcnt lgkmcnt(6)
	v_mfma_f32_32x32x16_bf16 v[80:95], v[120:123], v[184:187], v[80:95]
	ds_read_b128 v[120:123], v101 offset:61696
	s_waitcnt lgkmcnt(6)
	v_mfma_f32_32x32x16_bf16 v[64:79], v[124:127], v[184:187], v[64:79]
	ds_read_b128 v[124:127], v102 offset:49408
	s_waitcnt lgkmcnt(6)
	v_mfma_f32_32x32x16_bf16 v[80:95], v[96:99], v[188:191], v[80:95]
	ds_read_b128 v[96:99], v102 offset:61696
	s_waitcnt lgkmcnt(6)
	v_mfma_f32_32x32x16_bf16 v[64:79], v[104:107], v[188:191], v[64:79]
	ds_read_b128 v[104:107], v103 offset:49408
	s_waitcnt lgkmcnt(6)
	v_mfma_f32_32x32x16_bf16 v[80:95], v[108:111], v[192:195], v[80:95]
	ds_read_b128 v[108:111], v103 offset:61696
	s_waitcnt lgkmcnt(6)
	v_mfma_f32_32x32x16_bf16 v[64:79], v[112:115], v[192:195], v[64:79]
	s_waitcnt lgkmcnt(5)
	v_mfma_f32_32x32x16_bf16 v[80:95], v[116:119], v[196:199], v[80:95]
	s_waitcnt lgkmcnt(4)
	v_mfma_f32_32x32x16_bf16 v[64:79], v[120:123], v[196:199], v[64:79]
	s_waitcnt lgkmcnt(3)
	v_mfma_f32_32x32x16_bf16 v[80:95], v[124:127], v[200:203], v[80:95]
	s_waitcnt lgkmcnt(2)
	v_mfma_f32_32x32x16_bf16 v[64:79], v[96:99], v[200:203], v[64:79]
	s_waitcnt lgkmcnt(1)
	v_mfma_f32_32x32x16_bf16 v[80:95], v[104:107], v[204:207], v[80:95]
	s_waitcnt lgkmcnt(0)
	v_mfma_f32_32x32x16_bf16 v[64:79], v[108:111], v[204:207], v[64:79]
	s_cbranch_scc1 .LBB0_343
	v_add_u32_e32 v96, 27, v248
	v_cmp_lt_i32_e32 vcc, -1, v96
	s_nop 5
	v_cndmask_b32_e32 v80, v225, v80, vcc
	v_cmp_lt_i32_e32 vcc, 31, v96
	v_add_u32_e32 v96, 26, v248
	s_nop 0
	v_cndmask_b32_e32 v64, v225, v64, vcc
	v_cmp_lt_i32_e32 vcc, -1, v96
	s_nop 1
	v_cndmask_b32_e32 v81, v225, v81, vcc
	v_cmp_lt_i32_e32 vcc, 31, v96
	v_add_u32_e32 v96, 25, v248
	s_nop 0
	v_cndmask_b32_e32 v65, v225, v65, vcc
	v_cmp_lt_i32_e32 vcc, -1, v96
	s_nop 1
	v_cndmask_b32_e32 v82, v225, v82, vcc
	v_cmp_lt_i32_e32 vcc, 31, v96
	v_add_u32_e32 v96, 24, v248
	s_nop 0
	v_cndmask_b32_e32 v66, v225, v66, vcc
	v_cmp_lt_i32_e32 vcc, -1, v96
	s_nop 1
	v_cndmask_b32_e32 v83, v225, v83, vcc
	v_cmp_lt_i32_e32 vcc, 31, v96
	v_add_u32_e32 v96, 19, v248
	s_nop 0
	v_cndmask_b32_e32 v67, v225, v67, vcc
	v_cmp_lt_i32_e32 vcc, -1, v96
	s_nop 1
	v_cndmask_b32_e32 v84, v225, v84, vcc
	v_cmp_lt_i32_e32 vcc, 31, v96
	v_add_u32_e32 v96, 18, v248
	s_nop 0
	v_cndmask_b32_e32 v68, v225, v68, vcc
	v_cmp_lt_i32_e32 vcc, -1, v96
	s_nop 1
	v_cndmask_b32_e32 v85, v225, v85, vcc
	v_cmp_lt_i32_e32 vcc, 31, v96
	v_add_u32_e32 v96, 17, v248
	s_nop 0
	v_cndmask_b32_e32 v69, v225, v69, vcc
	v_cmp_lt_i32_e32 vcc, -1, v96
	s_nop 1
	v_cndmask_b32_e32 v86, v225, v86, vcc
	v_cmp_lt_i32_e32 vcc, 31, v96
	v_add_u32_e32 v96, 16, v248
	s_nop 0
	v_cndmask_b32_e32 v70, v225, v70, vcc
	v_cmp_lt_i32_e32 vcc, -1, v96
	s_nop 1
	v_cndmask_b32_e32 v87, v225, v87, vcc
	v_cmp_lt_i32_e32 vcc, 31, v96
	v_add_u32_e32 v96, 11, v248
	s_nop 0
	v_cndmask_b32_e32 v71, v225, v71, vcc
	v_cmp_lt_i32_e32 vcc, -1, v96
	s_nop 1
	v_cndmask_b32_e32 v88, v225, v88, vcc
	v_cmp_lt_i32_e32 vcc, 31, v96
	v_add_u32_e32 v96, 10, v248
	s_nop 0
	v_cndmask_b32_e32 v72, v225, v72, vcc
	v_cmp_lt_i32_e32 vcc, -1, v96
	s_nop 1
	v_cndmask_b32_e32 v89, v225, v89, vcc
	v_cmp_lt_i32_e32 vcc, 31, v96
	v_add_u32_e32 v96, 9, v248
	s_nop 0
	v_cndmask_b32_e32 v73, v225, v73, vcc
	v_cmp_lt_i32_e32 vcc, -1, v96
	s_nop 1
	v_cndmask_b32_e32 v90, v225, v90, vcc
	v_cmp_lt_i32_e32 vcc, 31, v96
	v_add_u32_e32 v96, 8, v248
	s_nop 0
	v_cndmask_b32_e32 v74, v225, v74, vcc
	v_cmp_lt_i32_e32 vcc, -1, v96
	s_nop 1
	v_cndmask_b32_e32 v91, v225, v91, vcc
	v_cmp_lt_i32_e32 vcc, 31, v96
	v_add_u32_e32 v96, 3, v248
	s_nop 0
	v_cndmask_b32_e32 v75, v225, v75, vcc
	v_cmp_lt_i32_e32 vcc, -1, v96
	s_nop 1
	v_cndmask_b32_e32 v92, v225, v92, vcc
	v_cmp_lt_i32_e32 vcc, 31, v96
	v_add_u32_e32 v96, 2, v248
	s_nop 0
	v_cndmask_b32_e32 v76, v225, v76, vcc
	v_cmp_lt_i32_e32 vcc, -1, v96
	s_nop 1
	v_cndmask_b32_e32 v93, v225, v93, vcc
	v_cmp_lt_i32_e32 vcc, 31, v96
	v_add_u32_e32 v96, 1, v248
	s_nop 0
	v_cndmask_b32_e32 v77, v225, v77, vcc
	v_cmp_lt_i32_e32 vcc, -1, v96
	s_nop 1
	v_cndmask_b32_e32 v94, v225, v94, vcc
	v_cmp_lt_i32_e32 vcc, 31, v96
	s_nop 1
	v_cndmask_b32_e32 v78, v225, v78, vcc
	v_cmp_lt_i32_e32 vcc, -1, v248
	s_nop 1
	v_cndmask_b32_e32 v95, v225, v95, vcc
	v_cmp_lt_i32_e32 vcc, 31, v248
	s_nop 1
	v_cndmask_b32_e32 v79, v225, v79, vcc

; #define PG8_STAGE(bufoff, gbase, voff) do { _Pragma("unroll") for (int _i = 0; _i < 2; ++_i) \
;         __builtin_amdgcn_global_load_lds((const unsigned*)((const char*)(gbase) + (voff)[_i]), (LAS unsigned*)(lds + (bufoff) + ldsw + _i * 8192), 16, 0, 0); } while (0)
; #define PG8_LDA(dst, b, h) do { _Pragma("unroll") for (int m = 0; m < 4; ++m) _Pragma("unroll") for (int k = 0; k < 2; ++k) dst[m][k] = *(const LAS bf16x8*)(lds + PG8_SA(b, h) + aoff + m * 2048 + k * 1024); } while (0)
; #define PG8_LDB(dst, b, h) do { _Pragma("unroll") for (int n = 0; n < 2; ++n) _Pragma("unroll") for (int k = 0; k < 2; ++k) dst[n][k] = *(const LAS bf16x8*)(lds + PG8_SB(b, h) + boff + n * 2048 + k * 1024); } while (0)
; #define PG8_MMA(ai, bj, At, Bt) do { __builtin_amdgcn_s_setprio(1); _Pragma("unroll") for (int m = 0; m < 4; ++m) _Pragma("unroll") for (int n = 0; n < 2; ++n) _Pragma("unroll") for (int k = 0; k < 2; ++k) \
;         acc[ai][bj][m][n] = __builtin_amdgcn_mfma_f32_16x16x32_bf16(Bt[n][k], At[m][k], acc[ai][bj][m][n], 0, 0, 0); __builtin_amdgcn_s_setprio(0); } while (0)
; #define PG8_WAIT_V(n) asm volatile("s_waitcnt vmcnt(" #n ")" ::: "memory")
; #define PG8_WAIT_L(n) asm volatile("s_waitcnt lgkmcnt(" #n ")" ::: "memory")
; #define PG8_BAR __builtin_amdgcn_s_barrier()
; #define PG8_SCHED __builtin_amdgcn_sched_barrier(0)
; template <class Epi>
; __device__ __forceinline__ void gemm_phase(LAS unsigned char* lds, const Gemm g, const Epi& E) {
;     ...
;             PG8_LDB(B0, 0, 0); PG8_SCHED; PG8_LDA(At, 0, 0); PG8_STAGE(PG8_SA(1, 1), a1 + hstep, voffA);
;             PG8_WAIT_L(8); PG8_BAR; PG8_WAIT_L(0); PG8_MMA(0, 0, At, B0); PG8_BAR; PG8_SCHED;
;             PG8_LDB(B1, 0, 1); PG8_STAGE(PG8_SB(0, 0), b2, voffB);
;             PG8_BAR; PG8_WAIT_L(0); PG8_MMA(0, 1, At, B1); PG8_BAR;
;             PG8_LDA(At, 0, 1); PG8_STAGE(PG8_SA(0, 0), a2, voffA);
;             PG8_BAR; PG8_WAIT_L(0); PG8_MMA(1, 0, At, B0); PG8_BAR; PG8_SCHED;
;             PG8_STAGE(PG8_SB(0, 1), b2 + hstep, voffB);
;             PG8_WAIT_V(6); PG8_BAR; PG8_MMA(1, 1, At, B1); PG8_BAR;
.LBB0_499:
	s_add_u32 s28, s26, 0xfffe0080
	s_addc_u32 s29, s27, -1
	s_add_i32 s34, 0, 0x10000
	v_add_u32_e32 v156, s34, v159
	ds_read_b128 v[144:147], v156
	ds_read_b128 v[148:151], v156 offset:1024
	ds_read_b128 v[152:155], v156 offset:2048
	ds_read_b128 v[162:165], v156 offset:3072
	s_cmp_eq_u32 vcc_lo, 4
	s_cselect_b32 s37, s1, s29
	s_cselect_b32 s36, s31, s28
	s_cselect_b32 s29, s42, s65
	s_cselect_b32 s28, s43, s45
	v_lshl_add_u64 v[156:157], s[26:27], 0, v[140:141]
	s_add_i32 m0, s95, 0xc000
	ds_read_b128 v[166:169], v161
	ds_read_b128 v[170:173], v161 offset:1024
	ds_read_b128 v[174:177], v161 offset:2048
	ds_read_b128 v[178:181], v161 offset:3072
	ds_read_b128 v[182:185], v161 offset:4096
	ds_read_b128 v[186:189], v161 offset:5120
	ds_read_b128 v[190:193], v161 offset:6144
	ds_read_b128 v[194:197], v161 offset:7168
	global_load_lds_dwordx4 v[156:157], off
	v_lshl_add_u64 v[156:157], s[26:27], 0, v[142:143]
	s_add_i32 m0, s95, 0xe000
	s_nop 0
	global_load_lds_dwordx4 v[156:157], off
	s_waitcnt lgkmcnt(8)
	s_barrier
	s_waitcnt lgkmcnt(0)
	s_setprio 1
	s_waitcnt lgkmcnt(0)
	v_mfma_f32_16x16x32_bf16 v[124:127], v[144:147], v[166:169], v[124:127]
	v_mfma_f32_16x16x32_bf16 v[120:123], v[152:155], v[166:169], v[120:123]
	v_mfma_f32_16x16x32_bf16 v[108:111], v[144:147], v[174:177], v[108:111]
	v_mfma_f32_16x16x32_bf16 v[104:107], v[152:155], v[174:177], v[104:107]
	v_mfma_f32_16x16x32_bf16 v[92:95], v[144:147], v[182:185], v[92:95]
	v_mfma_f32_16x16x32_bf16 v[88:91], v[152:155], v[182:185], v[88:91]
	v_mfma_f32_16x16x32_bf16 v[76:79], v[144:147], v[190:193], v[76:79]
	v_mfma_f32_16x16x32_bf16 v[72:75], v[152:155], v[190:193], v[72:75]
	v_mfma_f32_16x16x32_bf16 v[124:127], v[148:151], v[170:173], v[124:127]
	v_mfma_f32_16x16x32_bf16 v[120:123], v[162:165], v[170:173], v[120:123]
	v_mfma_f32_16x16x32_bf16 v[108:111], v[148:151], v[178:181], v[108:111]
	v_mfma_f32_16x16x32_bf16 v[104:107], v[162:165], v[178:181], v[104:107]
	v_mfma_f32_16x16x32_bf16 v[92:95], v[148:151], v[186:189], v[92:95]
	v_mfma_f32_16x16x32_bf16 v[88:91], v[162:165], v[186:189], v[88:91]
	v_mfma_f32_16x16x32_bf16 v[76:79], v[148:151], v[194:197], v[76:79]
	v_mfma_f32_16x16x32_bf16 v[72:75], v[162:165], v[194:197], v[72:75]
	s_setprio 0
	s_barrier
	s_add_i32 vcc_hi, 0, 0x14000
	v_add_u32_e32 v156, vcc_hi, v159
	s_add_i32 s34, s34, s83
	ds_read_b128 v[198:201], v156
	ds_read_b128 v[202:205], v156 offset:1024
	ds_read_b128 v[238:241], v156 offset:2048
	ds_read_b128 v[242:245], v156 offset:3072
	v_lshl_add_u64 v[156:157], s[28:29], 0, v[130:131]
	s_mov_b32 m0, s34
	v_lshl_add_u64 v[206:207], s[28:29], 0, v[134:135]
	global_load_lds_dwordx4 v[156:157], off
	s_add_i32 m0, s34, 0x2000
	s_nop 0
	global_load_lds_dwordx4 v[206:207], off
	s_barrier
	s_waitcnt lgkmcnt(0)
	s_setprio 1
	s_waitcnt lgkmcnt(0)
	v_mfma_f32_16x16x32_bf16 v[116:119], v[198:201], v[166:169], v[116:119]
	v_mfma_f32_16x16x32_bf16 v[112:115], v[238:241], v[166:169], v[112:115]
	v_mfma_f32_16x16x32_bf16 v[100:103], v[198:201], v[174:177], v[100:103]
	v_mfma_f32_16x16x32_bf16 v[96:99], v[238:241], v[174:177], v[96:99]
	v_mfma_f32_16x16x32_bf16 v[84:87], v[198:201], v[182:185], v[84:87]
	v_mfma_f32_16x16x32_bf16 v[80:83], v[238:241], v[182:185], v[80:83]
	v_mfma_f32_16x16x32_bf16 v[68:71], v[198:201], v[190:193], v[68:71]
	v_mfma_f32_16x16x32_bf16 v[64:67], v[238:241], v[190:193], v[64:67]
	v_mfma_f32_16x16x32_bf16 v[116:119], v[202:205], v[170:173], v[116:119]
	v_mfma_f32_16x16x32_bf16 v[112:115], v[242:245], v[170:173], v[112:115]
	v_mfma_f32_16x16x32_bf16 v[100:103], v[202:205], v[178:181], v[100:103]
	v_mfma_f32_16x16x32_bf16 v[96:99], v[242:245], v[178:181], v[96:99]
	v_mfma_f32_16x16x32_bf16 v[84:87], v[202:205], v[186:189], v[84:87]
	v_mfma_f32_16x16x32_bf16 v[80:83], v[242:245], v[186:189], v[80:83]
	v_mfma_f32_16x16x32_bf16 v[68:71], v[202:205], v[194:197], v[68:71]
	v_mfma_f32_16x16x32_bf16 v[64:67], v[242:245], v[194:197], v[64:67]
	s_setprio 0
	s_mov_b32 m0, s95
	v_lshl_add_u64 v[220:221], s[36:37], 0, v[128:129]
	s_barrier
	ds_read_b128 v[166:169], v161 offset:16384
	ds_read_b128 v[170:173], v161 offset:17408
	ds_read_b128 v[174:177], v161 offset:18432
	ds_read_b128 v[178:181], v161 offset:19456
	ds_read_b128 v[182:185], v161 offset:20480
	ds_read_b128 v[186:189], v161 offset:21504
	ds_read_b128 v[190:193], v161 offset:22528
	ds_read_b128 v[194:197], v161 offset:23552
	global_load_lds_dwordx4 v[220:221], off
	v_lshl_add_u64 v[228:229], s[36:37], 0, v[132:133]
	s_mov_b32 m0, s82
	s_nop 0
	global_load_lds_dwordx4 v[228:229], off
	s_barrier
	s_waitcnt lgkmcnt(0)
	s_setprio 1
	s_waitcnt lgkmcnt(0)
	v_mfma_f32_16x16x32_bf16 v[60:63], v[144:147], v[166:169], v[60:63]
	v_mfma_f32_16x16x32_bf16 v[56:59], v[152:155], v[166:169], v[56:59]
	v_mfma_f32_16x16x32_bf16 v[44:47], v[144:147], v[174:177], v[44:47]
	v_mfma_f32_16x16x32_bf16 v[40:43], v[152:155], v[174:177], v[40:43]
	v_mfma_f32_16x16x32_bf16 v[28:31], v[144:147], v[182:185], v[28:31]
	v_mfma_f32_16x16x32_bf16 v[24:27], v[152:155], v[182:185], v[24:27]
	v_mfma_f32_16x16x32_bf16 v[12:15], v[144:147], v[190:193], v[12:15]
	v_mfma_f32_16x16x32_bf16 v[8:11], v[152:155], v[190:193], v[8:11]
	v_mfma_f32_16x16x32_bf16 v[60:63], v[148:151], v[170:173], v[60:63]
	v_mfma_f32_16x16x32_bf16 v[56:59], v[162:165], v[170:173], v[56:59]
	v_mfma_f32_16x16x32_bf16 v[44:47], v[148:151], v[178:181], v[44:47]
	v_mfma_f32_16x16x32_bf16 v[40:43], v[162:165], v[178:181], v[40:43]
	v_mfma_f32_16x16x32_bf16 v[28:31], v[148:151], v[186:189], v[28:31]
	v_mfma_f32_16x16x32_bf16 v[24:27], v[162:165], v[186:189], v[24:27]
	v_mfma_f32_16x16x32_bf16 v[12:15], v[148:151], v[194:197], v[12:15]
	v_mfma_f32_16x16x32_bf16 v[8:11], v[162:165], v[194:197], v[8:11]
	s_setprio 0
	s_barrier
; #define PG8_STAGE(bufoff, gbase, voff) do { _Pragma("unroll") for (int _i = 0; _i < 2; ++_i) \
;         __builtin_amdgcn_global_load_lds((const unsigned*)((const char*)(gbase) + (voff)[_i]), (LAS unsigned*)(lds + (bufoff) + ldsw + _i * 8192), 16, 0, 0); } while (0)
; #define PG8_LDA(dst, b, h) do { _Pragma("unroll") for (int m = 0; m < 4; ++m) _Pragma("unroll") for (int k = 0; k < 2; ++k) dst[m][k] = *(const LAS bf16x8*)(lds + PG8_SA(b, h) + aoff + m * 2048 + k * 1024); } while (0)
; #define PG8_LDB(dst, b, h) do { _Pragma("unroll") for (int n = 0; n < 2; ++n) _Pragma("unroll") for (int k = 0; k < 2; ++k) dst[n][k] = *(const LAS bf16x8*)(lds + PG8_SB(b, h) + boff + n * 2048 + k * 1024); } while (0)
; #define PG8_MMA(ai, bj, At, Bt) do { __builtin_amdgcn_s_setprio(1); _Pragma("unroll") for (int m = 0; m < 4; ++m) _Pragma("unroll") for (int n = 0; n < 2; ++n) _Pragma("unroll") for (int k = 0; k < 2; ++k) \
;         acc[ai][bj][m][n] = __builtin_amdgcn_mfma_f32_16x16x32_bf16(Bt[n][k], At[m][k], acc[ai][bj][m][n], 0, 0, 0); __builtin_amdgcn_s_setprio(0); } while (0)
; #define PG8_WAIT_V(n) asm volatile("s_waitcnt vmcnt(" #n ")" ::: "memory")
; #define PG8_WAIT_L(n) asm volatile("s_waitcnt lgkmcnt(" #n ")" ::: "memory")
; #define PG8_BAR __builtin_amdgcn_s_barrier()
; #define PG8_SCHED __builtin_amdgcn_sched_barrier(0)
; template <class Epi>
; __device__ __forceinline__ void gemm_phase(LAS unsigned char* lds, const Gemm g, const Epi& E) {
;     ...
;             PG8_STAGE(PG8_SB(0, 1), b2 + hstep, voffB);
;             PG8_WAIT_V(6); PG8_BAR; PG8_MMA(1, 1, At, B1); PG8_BAR;
;             PG8_LDB(B0, 1, 0); PG8_SCHED; PG8_LDA(At, 1, 0); PG8_STAGE(PG8_SA(0, 1), a2 + hstep, voffA);
;             PG8_WAIT_L(8); PG8_BAR; PG8_WAIT_L(0); PG8_MMA(0, 0, At, B0); PG8_BAR; PG8_SCHED;
;             PG8_LDB(B1, 1, 1); PG8_STAGE(PG8_SB(1, 0), b3, voffB);
;             PG8_BAR; PG8_WAIT_L(0); PG8_MMA(0, 1, At, B1); PG8_BAR;
;             PG8_LDA(At, 1, 1); PG8_STAGE(PG8_SA(1, 0), a3, voffA);
;             PG8_BAR; PG8_WAIT_L(0); PG8_MMA(1, 0, At, B0); PG8_BAR; PG8_SCHED;
	s_add_u32 s34, s28, 0x20000
	s_addc_u32 s35, s29, 0
	s_add_i32 vcc_hi, vcc_hi, s83
	v_lshl_add_u64 v[144:145], s[34:35], 0, v[130:131]
	s_mov_b32 m0, vcc_hi
	s_nop 0
	global_load_lds_dwordx4 v[144:145], off
	v_lshl_add_u64 v[144:145], s[34:35], 0, v[134:135]
	s_add_i32 m0, vcc_hi, 0x2000
	s_nop 0
	global_load_lds_dwordx4 v[144:145], off
	s_waitcnt vmcnt(6)
	s_barrier
	s_setprio 1
	v_mfma_f32_16x16x32_bf16 v[52:55], v[198:201], v[166:169], v[52:55]
	v_mfma_f32_16x16x32_bf16 v[48:51], v[238:241], v[166:169], v[48:51]
	v_mfma_f32_16x16x32_bf16 v[36:39], v[198:201], v[174:177], v[36:39]
	v_mfma_f32_16x16x32_bf16 v[32:35], v[238:241], v[174:177], v[32:35]
	v_mfma_f32_16x16x32_bf16 v[20:23], v[198:201], v[182:185], v[20:23]
	v_mfma_f32_16x16x32_bf16 v[16:19], v[238:241], v[182:185], v[16:19]
	v_mfma_f32_16x16x32_bf16 v[4:7], v[198:201], v[190:193], v[4:7]
	v_mfma_f32_16x16x32_bf16 v[0:3], v[238:241], v[190:193], v[0:3]
	v_mfma_f32_16x16x32_bf16 v[52:55], v[202:205], v[170:173], v[52:55]
	v_mfma_f32_16x16x32_bf16 v[48:51], v[242:245], v[170:173], v[48:51]
	v_mfma_f32_16x16x32_bf16 v[36:39], v[202:205], v[178:181], v[36:39]
	v_mfma_f32_16x16x32_bf16 v[32:35], v[242:245], v[178:181], v[32:35]
	v_mfma_f32_16x16x32_bf16 v[20:23], v[202:205], v[186:189], v[20:23]
	v_mfma_f32_16x16x32_bf16 v[16:19], v[242:245], v[186:189], v[16:19]
	v_mfma_f32_16x16x32_bf16 v[4:7], v[202:205], v[194:197], v[4:7]
	v_mfma_f32_16x16x32_bf16 v[0:3], v[242:245], v[194:197], v[0:3]
	s_setprio 0
	s_add_i32 vcc_hi, 0, 0x18000
	v_add_u32_e32 v162, vcc_hi, v159
	s_barrier
	ds_read_b128 v[144:147], v162
	ds_read_b128 v[148:151], v162 offset:1024
	ds_read_b128 v[152:155], v162 offset:2048
	ds_read_b128 v[162:165], v162 offset:3072
	s_add_u32 s34, s36, 0x20000
	s_addc_u32 s35, s37, 0
	s_mov_b32 m0, s78
	v_lshl_add_u64 v[198:199], s[34:35], 0, v[128:129]
	ds_read_b128 v[166:169], v161 offset:32768
	ds_read_b128 v[170:173], v161 offset:33792
	ds_read_b128 v[174:177], v161 offset:34816
	ds_read_b128 v[178:181], v161 offset:35840
	ds_read_b128 v[182:185], v161 offset:36864
	ds_read_b128 v[186:189], v161 offset:37888
	ds_read_b128 v[190:193], v161 offset:38912
	ds_read_b128 v[194:197], v161 offset:39936
	global_load_lds_dwordx4 v[198:199], off
	v_lshl_add_u64 v[198:199], s[34:35], 0, v[132:133]
	s_mov_b32 m0, s76
	s_nop 0
	global_load_lds_dwordx4 v[198:199], off
	s_waitcnt lgkmcnt(8)
	s_barrier
	s_waitcnt lgkmcnt(0)
	s_setprio 1
	s_waitcnt lgkmcnt(0)
	v_mfma_f32_16x16x32_bf16 v[124:127], v[144:147], v[166:169], v[124:127]
	v_mfma_f32_16x16x32_bf16 v[120:123], v[152:155], v[166:169], v[120:123]
	v_mfma_f32_16x16x32_bf16 v[108:111], v[144:147], v[174:177], v[108:111]
	v_mfma_f32_16x16x32_bf16 v[104:107], v[152:155], v[174:177], v[104:107]
	v_mfma_f32_16x16x32_bf16 v[92:95], v[144:147], v[182:185], v[92:95]
	v_mfma_f32_16x16x32_bf16 v[88:91], v[152:155], v[182:185], v[88:91]
	v_mfma_f32_16x16x32_bf16 v[76:79], v[144:147], v[190:193], v[76:79]
	v_mfma_f32_16x16x32_bf16 v[72:75], v[152:155], v[190:193], v[72:75]
	v_mfma_f32_16x16x32_bf16 v[124:127], v[148:151], v[170:173], v[124:127]
	v_mfma_f32_16x16x32_bf16 v[120:123], v[162:165], v[170:173], v[120:123]
	v_mfma_f32_16x16x32_bf16 v[108:111], v[148:151], v[178:181], v[108:111]
	v_mfma_f32_16x16x32_bf16 v[104:107], v[162:165], v[178:181], v[104:107]
	v_mfma_f32_16x16x32_bf16 v[92:95], v[148:151], v[186:189], v[92:95]
	v_mfma_f32_16x16x32_bf16 v[88:91], v[162:165], v[186:189], v[88:91]
	v_mfma_f32_16x16x32_bf16 v[76:79], v[148:151], v[194:197], v[76:79]
	v_mfma_f32_16x16x32_bf16 v[72:75], v[162:165], v[194:197], v[72:75]
	s_setprio 0
	s_barrier
	s_add_i32 s34, 0, 0x1c000
	s_add_i32 s35, vcc_hi, s83
	v_add_u32_e32 v208, s34, v159
	v_lshl_add_u64 v[156:157], v[156:157], 0, s[20:21]
	s_mov_b32 m0, s35
	ds_read_b128 v[198:201], v208
	ds_read_b128 v[202:205], v208 offset:1024
	ds_read_b128 v[238:241], v208 offset:2048
	ds_read_b128 v[242:245], v208 offset:3072
	global_load_lds_dwordx4 v[156:157], off
	v_lshl_add_u64 v[156:157], v[206:207], 0, s[20:21]
	s_add_i32 m0, s35, 0x2000
	s_nop 0
	global_load_lds_dwordx4 v[156:157], off
	s_barrier
	s_waitcnt lgkmcnt(0)
	s_setprio 1
	s_waitcnt lgkmcnt(0)
	v_mfma_f32_16x16x32_bf16 v[116:119], v[198:201], v[166:169], v[116:119]
	v_mfma_f32_16x16x32_bf16 v[112:115], v[238:241], v[166:169], v[112:115]
	v_mfma_f32_16x16x32_bf16 v[100:103], v[198:201], v[174:177], v[100:103]
	v_mfma_f32_16x16x32_bf16 v[96:99], v[238:241], v[174:177], v[96:99]
	v_mfma_f32_16x16x32_bf16 v[84:87], v[198:201], v[182:185], v[84:87]
	v_mfma_f32_16x16x32_bf16 v[80:83], v[238:241], v[182:185], v[80:83]
	v_mfma_f32_16x16x32_bf16 v[68:71], v[198:201], v[190:193], v[68:71]
	v_mfma_f32_16x16x32_bf16 v[64:67], v[238:241], v[190:193], v[64:67]
	v_mfma_f32_16x16x32_bf16 v[116:119], v[202:205], v[170:173], v[116:119]
	v_mfma_f32_16x16x32_bf16 v[112:115], v[242:245], v[170:173], v[112:115]
	v_mfma_f32_16x16x32_bf16 v[100:103], v[202:205], v[178:181], v[100:103]
	v_mfma_f32_16x16x32_bf16 v[96:99], v[242:245], v[178:181], v[96:99]
	v_mfma_f32_16x16x32_bf16 v[84:87], v[202:205], v[186:189], v[84:87]
	v_mfma_f32_16x16x32_bf16 v[80:83], v[242:245], v[186:189], v[80:83]
	v_mfma_f32_16x16x32_bf16 v[68:71], v[202:205], v[194:197], v[68:71]
	v_mfma_f32_16x16x32_bf16 v[64:67], v[242:245], v[194:197], v[64:67]
	s_setprio 0
	s_mov_b32 m0, s68
	v_lshl_add_u64 v[156:157], v[220:221], 0, s[20:21]
	s_barrier
; __device__ __forceinline__ u32x4 pack8u(f32x4 a, f32x4 b) { u32x4 w = {cvt_pk_bf16(a[0], a[1]), cvt_pk_bf16(a[2], a[3]), cvt_pk_bf16(b[0], b[1]), cvt_pk_bf16(b[2], b[3])}; return w; }
; __device__ __forceinline__ u32x2 pack4u(f32x4 a) { u32x2 w = {cvt_pk_bf16(a[0], a[1]), cvt_pk_bf16(a[2], a[3])}; return w; }
; #define PG8_WAIT_V(n) asm volatile("s_waitcnt vmcnt(" #n ")" ::: "memory")
; #define PG8_WAIT_L(n) asm volatile("s_waitcnt lgkmcnt(" #n ")" ::: "memory")
; template <class Epi>
; __device__ __forceinline__ void gemm_phase(LAS unsigned char* lds, const Gemm g, const Epi& E) {
;     ...
;             PG8_BAR; PG8_WAIT_L(0); PG8_MMA(1, 0, At, B0); PG8_BAR; PG8_SCHED;
;             PG8_STAGE(PG8_SB(1, 1), b3 + hstep, voffB);
;             PG8_WAIT_V(6); PG8_BAR; PG8_MMA(1, 1, At, B1); PG8_BAR;
;         }
;     __device__ __forceinline__ void operator()(const AccT& acc, const Unit& u, int wr, int wc, int fr, int fq) const {
;     ...
;                 const int row = u.pm * 256 + ai * 128 + wr * 64 + m * 16 + fr; const int b = row / SEQ, t = row % SEQ;
;                 const f32x4 s0 = *(const f32x4*)(SSQ + (size_t)row * 16 + mode * 8), s1 = *(const f32x4*)(SSQ + (size_t)row * 16 + mode * 8 + 4);
;                 const float ssq = (s0[0] + s0[1]) + (s0[2] + s0[3]) + (s1[0] + s1[1]) + (s1[2] + s1[3]);
;                 float rs = rsqrtf(ssq * (1.0f / 512.0f) + EPS);
;                 if (mode == 0) {
;                     rs *= (0.07216878364870322f * 1.4426950408889634f);
; #pragma unroll
;                     for (int bj = 0; bj < 2; ++bj) {
;                         const int c8 = u.pn * 256 + bj * 128 + wc * 32 + fq * 8; const int head = c8 / DQK, d0 = c8 % DQK;
;                         bf16_t* qp = Q + ((size_t)(b * NH + head) * SEQ + t) * DQK;
;                         const f32x4 v0 = acc[ai][bj][m][0] * rs, v1 = acc[ai][bj][m][1] * rs;
;                         if (d0 < 128) { *(u32x4*)(qp + d0) = pack8u(v0, v1); }
;                         else { const int i0 = 4 * ((d0 - 128) >> 3);
;                             const f32x4 cs = *(const f32x4*)(COS + (size_t)row * 32 + i0), sn = *(const f32x4*)(SIN + (size_t)row * 32 + i0);
;                             const f32x4 o1 = v0 * cs - v1 * sn, o2 = v1 * cs + v0 * sn;
;                             *(u32x2*)(qp + 128 + i0) = pack4u(o1); *(u32x2*)(qp + 160 + i0) = pack4u(o2); }
	ds_read_b128 v[166:169], v161 offset:49152
	ds_read_b128 v[170:173], v161 offset:50176
	ds_read_b128 v[174:177], v161 offset:51200
	ds_read_b128 v[178:181], v161 offset:52224
	ds_read_b128 v[182:185], v161 offset:53248
	ds_read_b128 v[186:189], v161 offset:54272
	ds_read_b128 v[190:193], v161 offset:55296
	ds_read_b128 v[194:197], v161 offset:56320
	global_load_lds_dwordx4 v[156:157], off
	v_lshl_add_u64 v[156:157], v[228:229], 0, s[20:21]
	s_mov_b32 m0, s74
	s_nop 0
	global_load_lds_dwordx4 v[156:157], off
	s_barrier
	s_waitcnt lgkmcnt(0)
	s_setprio 1
	s_waitcnt lgkmcnt(0)
	v_mfma_f32_16x16x32_bf16 v[60:63], v[144:147], v[166:169], v[60:63]
	v_mfma_f32_16x16x32_bf16 v[56:59], v[152:155], v[166:169], v[56:59]
	v_mfma_f32_16x16x32_bf16 v[44:47], v[144:147], v[174:177], v[44:47]
	v_mfma_f32_16x16x32_bf16 v[40:43], v[152:155], v[174:177], v[40:43]
	v_mfma_f32_16x16x32_bf16 v[28:31], v[144:147], v[182:185], v[28:31]
	v_mfma_f32_16x16x32_bf16 v[24:27], v[152:155], v[182:185], v[24:27]
	v_mfma_f32_16x16x32_bf16 v[12:15], v[144:147], v[190:193], v[12:15]
	v_mfma_f32_16x16x32_bf16 v[8:11], v[152:155], v[190:193], v[8:11]
	v_mfma_f32_16x16x32_bf16 v[60:63], v[148:151], v[170:173], v[60:63]
	v_mfma_f32_16x16x32_bf16 v[56:59], v[162:165], v[170:173], v[56:59]
	v_mfma_f32_16x16x32_bf16 v[44:47], v[148:151], v[178:181], v[44:47]
	v_mfma_f32_16x16x32_bf16 v[40:43], v[162:165], v[178:181], v[40:43]
	v_mfma_f32_16x16x32_bf16 v[28:31], v[148:151], v[186:189], v[28:31]
	v_mfma_f32_16x16x32_bf16 v[24:27], v[162:165], v[186:189], v[24:27]
	v_mfma_f32_16x16x32_bf16 v[12:15], v[148:151], v[194:197], v[12:15]
	v_mfma_f32_16x16x32_bf16 v[8:11], v[162:165], v[194:197], v[8:11]
	s_setprio 0
	s_barrier
	s_add_u32 s28, s28, 0x20080
	s_addc_u32 s29, s29, 0
	s_add_i32 s34, s34, s83
	v_lshl_add_u64 v[144:145], s[28:29], 0, v[130:131]
	s_mov_b32 m0, s34
	s_nop 0
	global_load_lds_dwordx4 v[144:145], off
	v_lshl_add_u64 v[144:145], s[28:29], 0, v[134:135]
	s_add_i32 m0, s34, 0x2000
	s_nop 0
	global_load_lds_dwordx4 v[144:145], off
	s_waitcnt vmcnt(6)
	s_barrier
	s_setprio 1
	v_mfma_f32_16x16x32_bf16 v[52:55], v[198:201], v[166:169], v[52:55]
	v_mfma_f32_16x16x32_bf16 v[48:51], v[238:241], v[166:169], v[48:51]
	v_mfma_f32_16x16x32_bf16 v[36:39], v[198:201], v[174:177], v[36:39]
	v_mfma_f32_16x16x32_bf16 v[32:35], v[238:241], v[174:177], v[32:35]
	v_mfma_f32_16x16x32_bf16 v[20:23], v[198:201], v[182:185], v[20:23]
	v_mfma_f32_16x16x32_bf16 v[16:19], v[238:241], v[182:185], v[16:19]
	v_mfma_f32_16x16x32_bf16 v[4:7], v[198:201], v[190:193], v[4:7]
	v_mfma_f32_16x16x32_bf16 v[0:3], v[238:241], v[190:193], v[0:3]
	v_mfma_f32_16x16x32_bf16 v[52:55], v[202:205], v[170:173], v[52:55]
	v_mfma_f32_16x16x32_bf16 v[48:51], v[242:245], v[170:173], v[48:51]
	v_mfma_f32_16x16x32_bf16 v[36:39], v[202:205], v[178:181], v[36:39]
	v_mfma_f32_16x16x32_bf16 v[32:35], v[242:245], v[178:181], v[32:35]
	v_mfma_f32_16x16x32_bf16 v[20:23], v[202:205], v[186:189], v[20:23]
	v_mfma_f32_16x16x32_bf16 v[16:19], v[242:245], v[186:189], v[16:19]
	v_mfma_f32_16x16x32_bf16 v[4:7], v[202:205], v[194:197], v[4:7]
	v_mfma_f32_16x16x32_bf16 v[0:3], v[242:245], v[194:197], v[0:3]
	s_setprio 0
	s_add_i32 vcc_lo, vcc_lo, 2
	s_add_u32 s26, s26, 0x100
	s_addc_u32 s27, s27, 0
	s_add_u32 s45, s45, 0x100
	s_addc_u32 s65, s65, 0
	s_cmp_gt_u32 vcc_lo, 5
	s_barrier
	s_cbranch_scc0 .LBB0_499
	v_lshl_add_u32 v144, s0, 8, v158
	v_lshlrev_b32_e32 v220, 6, v144
	v_add_u32_e32 v221, 0x2000, v220
	global_load_dwordx4 v[176:179], v220, s[48:49] offset:16
	global_load_dwordx4 v[180:183], v220, s[48:49]
	global_load_dwordx4 v[184:187], v220, s[48:49] offset:1040
	global_load_dwordx4 v[188:191], v220, s[48:49] offset:1024
	global_load_dwordx4 v[192:195], v220, s[48:49] offset:2064
	global_load_dwordx4 v[196:199], v220, s[48:49] offset:2048
	global_load_dwordx4 v[200:203], v220, s[48:49] offset:3088
	global_load_dwordx4 v[204:207], v220, s[48:49] offset:3072
	v_ashrrev_i32_e32 v145, 31, v144
	v_lshlrev_b64 v[150:151], 6, v[144:145]
	v_lshl_add_u64 v[154:155], s[48:49], 0, v[150:151]
	s_waitcnt vmcnt(6)
	v_mov_b32_e32 v150, v176
	v_mov_b32_e32 v151, v177
	v_mov_b32_e32 v152, v178
	v_mov_b32_e32 v153, v179
	s_nop 0
	v_mov_b32_e32 v154, v180
	v_mov_b32_e32 v155, v181
	v_mov_b32_e32 v156, v182
	v_mov_b32_e32 v157, v183
	global_load_dwordx4 v[176:179], v221, s[48:49] offset:16
	global_load_dwordx4 v[180:183], v221, s[48:49]
	v_lshrrev_b32_e32 v146, 21, v145
	v_add_u32_e32 v146, v144, v146
	v_ashrrev_i32_e32 v149, 11, v146
	v_mul_i32_i24_e32 v146, 0x800, v149
	v_sub_u32_e32 v146, v144, v146
	s_mov_b64 s[0:1], -1
	s_nop 0
	v_mov_b32_e32 v162, v155
	v_mov_b32_e32 v163, v156
	v_mov_b32_e32 v155, v157
	v_pk_add_f32 v[154:155], v[162:163], v[154:155]
	v_mov_b32_e32 v156, v152
	v_mov_b32_e32 v157, v150
	v_mov_b32_e32 v150, v153
	v_pk_add_f32 v[150:151], v[156:157], v[150:151]
	v_add_f32_e32 v147, v154, v155
	v_add_f32_e32 v147, v147, v151
	v_add_f32_e32 v147, v150, v147
	v_fmamk_f32 v147, v147, 0x3b000000, v223
	v_cmp_gt_f32_e32 vcc, s60, v147
	v_mul_f32_e32 v148, 0x4b800000, v147
	s_nop 0
	v_cndmask_b32_e32 v147, v147, v148, vcc
	v_rsq_f32_e32 v147, v147
	s_nop 0
	v_mul_f32_e32 v148, 0x45800000, v147
	v_cndmask_b32_e32 v148, v147, v148, vcc
	s_and_b64 vcc, exec, s[46:47]
	v_ashrrev_i32_e32 v147, 31, v146
	s_cbranch_vccz .LBB0_502
	v_lshl_add_u32 v150, v149, 3, s94
	v_ashrrev_i32_e32 v151, 31, v150
	v_lshlrev_b64 v[150:151], 11, v[150:151]
	v_lshl_add_u64 v[154:155], v[150:151], 0, v[146:147]
	v_pk_mul_f32 v[152:153], v[126:127], v[148:149] op_sel_hi:[1,0]
	v_pk_mul_f32 v[150:151], v[124:125], v[148:149] op_sel_hi:[1,0]
	v_pk_mul_f32 v[156:157], v[122:123], v[148:149] op_sel_hi:[1,0]
	v_pk_mul_f32 v[162:163], v[120:121], v[148:149] op_sel_hi:[1,0]
	v_cvt_pk_bf16_f32 v150, v150, v151
	v_cvt_pk_bf16_f32 v151, v152, v153
	v_cvt_pk_bf16_f32 v153, v156, v157
	v_mad_u64_u32 v[156:157], s[0:1], v154, s33, v[136:137]
	v_cvt_pk_bf16_f32 v152, v162, v163
	v_mad_i32_i24 v157, v155, s33, v157
	global_store_dwordx4 v[156:157], v[150:153], off
	v_pk_mul_f32 v[156:157], v[114:115], v[148:149] op_sel_hi:[1,0]
	v_pk_mul_f32 v[162:163], v[112:113], v[148:149] op_sel_hi:[1,0]
	v_pk_mul_f32 v[152:153], v[118:119], v[148:149] op_sel_hi:[1,0]
	v_pk_mul_f32 v[150:151], v[116:117], v[148:149] op_sel_hi:[1,0]
	v_lshlrev_b64 v[154:155], 8, v[154:155]
	v_cvt_pk_bf16_f32 v150, v150, v151
	v_cvt_pk_bf16_f32 v151, v152, v153
	v_cvt_pk_bf16_f32 v152, v162, v163
	v_cvt_pk_bf16_f32 v153, v156, v157
	v_lshl_add_u64 v[154:155], v[138:139], 0, v[154:155]
	global_store_dwordx4 v[154:155], v[150:153], off
	s_mov_b64 s[0:1], 0

; __device__ __forceinline__ u32x4 pack8u(f32x4 a, f32x4 b) { u32x4 w = {cvt_pk_bf16(a[0], a[1]), cvt_pk_bf16(a[2], a[3]), cvt_pk_bf16(b[0], b[1]), cvt_pk_bf16(b[2], b[3])}; return w; }
; __device__ __forceinline__ u32x2 pack4u(f32x4 a) { u32x2 w = {cvt_pk_bf16(a[0], a[1]), cvt_pk_bf16(a[2], a[3])}; return w; }
;     __device__ __forceinline__ void operator()(const AccT& acc, const Unit& u, int wr, int wc, int fr, int fq) const {
;     ...
;                 const int row = u.pm * 256 + ai * 128 + wr * 64 + m * 16 + fr; const int b = row / SEQ, t = row % SEQ;
;                 const f32x4 s0 = *(const f32x4*)(SSQ + (size_t)row * 16 + mode * 8), s1 = *(const f32x4*)(SSQ + (size_t)row * 16 + mode * 8 + 4);
;                 const float ssq = (s0[0] + s0[1]) + (s0[2] + s0[3]) + (s1[0] + s1[1]) + (s1[2] + s1[3]);
;                 float rs = rsqrtf(ssq * (1.0f / 512.0f) + EPS);
;                 if (mode == 0) {
;                     rs *= (0.07216878364870322f * 1.4426950408889634f);
; #pragma unroll
;                     for (int bj = 0; bj < 2; ++bj) {
;                         const int c8 = u.pn * 256 + bj * 128 + wc * 32 + fq * 8; const int head = c8 / DQK, d0 = c8 % DQK;
;                         bf16_t* qp = Q + ((size_t)(b * NH + head) * SEQ + t) * DQK;
;                         const f32x4 v0 = acc[ai][bj][m][0] * rs, v1 = acc[ai][bj][m][1] * rs;
;                         if (d0 < 128) { *(u32x4*)(qp + d0) = pack8u(v0, v1); }
;                         else { const int i0 = 4 * ((d0 - 128) >> 3);
;                             const f32x4 cs = *(const f32x4*)(COS + (size_t)row * 32 + i0), sn = *(const f32x4*)(SIN + (size_t)row * 32 + i0);
;                             const f32x4 o1 = v0 * cs - v1 * sn, o2 = v1 * cs + v0 * sn;
;                             *(u32x2*)(qp + 128 + i0) = pack4u(o1); *(u32x2*)(qp + 160 + i0) = pack4u(o2); }
.LBB0_512:
	v_or_b32_e32 v114, 16, v144
	v_ashrrev_i32_e32 v115, 31, v114
	v_lshlrev_b64 v[118:119], 6, v[114:115]
	v_lshl_add_u64 v[122:123], s[48:49], 0, v[118:119]
	s_waitcnt vmcnt(6)
	v_mov_b32_e32 v118, v184
	v_mov_b32_e32 v119, v185
	v_mov_b32_e32 v120, v186
	v_mov_b32_e32 v121, v187
	v_mov_b32_e32 v146, v188
	v_mov_b32_e32 v147, v189
	v_mov_b32_e32 v148, v190
	v_mov_b32_e32 v149, v191
	global_load_dwordx4 v[184:187], v221, s[48:49] offset:1040
	global_load_dwordx4 v[188:191], v221, s[48:49] offset:1024
	v_ashrrev_i32_e32 v112, 31, v144
	v_lshrrev_b32_e32 v124, 21, v112
	v_add_u32_e32 v112, v114, v124
	v_ashrrev_i32_e32 v117, 11, v112
	v_mul_i32_i24_e32 v112, 0x800, v117
	v_sub_u32_e32 v112, v114, v112
	s_mov_b64 s[0:1], -1
	s_nop 0
	v_mov_b32_e32 v126, v120
	v_mov_b32_e32 v122, v147
	v_mov_b32_e32 v123, v148
	v_mov_b32_e32 v147, v149
	v_pk_add_f32 v[122:123], v[122:123], v[146:147]
	v_mov_b32_e32 v127, v118
	v_mov_b32_e32 v118, v121
	v_pk_add_f32 v[118:119], v[126:127], v[118:119]
	v_add_f32_e32 v113, v122, v123
	v_add_f32_e32 v113, v113, v119
	v_add_f32_e32 v113, v118, v113
	v_fmamk_f32 v113, v113, 0x3b000000, v223
	v_cmp_gt_f32_e32 vcc, s60, v113
	v_mul_f32_e32 v116, 0x4b800000, v113
	s_nop 0
	v_cndmask_b32_e32 v113, v113, v116, vcc
	v_rsq_f32_e32 v113, v113
	s_nop 0
	v_mul_f32_e32 v116, 0x45800000, v113
	v_cndmask_b32_e32 v116, v113, v116, vcc
	v_cndmask_b32_e64 v113, 0, 1, s[46:47]
	v_cmp_ne_u32_e64 s[42:43], 1, v113
	s_andn2_b64 vcc, exec, s[46:47]
	v_ashrrev_i32_e32 v113, 31, v112
	s_cbranch_vccnz .LBB0_514
	v_lshl_add_u32 v118, v117, 3, s94
	v_ashrrev_i32_e32 v119, 31, v118
	v_lshlrev_b64 v[118:119], 11, v[118:119]
	v_lshl_add_u64 v[122:123], v[118:119], 0, v[112:113]
	v_pk_mul_f32 v[120:121], v[110:111], v[116:117] op_sel_hi:[1,0]
	v_pk_mul_f32 v[118:119], v[108:109], v[116:117] op_sel_hi:[1,0]
	v_pk_mul_f32 v[126:127], v[106:107], v[116:117] op_sel_hi:[1,0]
	v_pk_mul_f32 v[146:147], v[104:105], v[116:117] op_sel_hi:[1,0]
	v_cvt_pk_bf16_f32 v118, v118, v119
	v_cvt_pk_bf16_f32 v119, v120, v121
	v_cvt_pk_bf16_f32 v121, v126, v127
	v_mad_u64_u32 v[126:127], s[0:1], v122, s33, v[136:137]
	v_cvt_pk_bf16_f32 v120, v146, v147
	v_mad_i32_i24 v127, v123, s33, v127
	global_store_dwordx4 v[126:127], v[118:121], off
	v_pk_mul_f32 v[126:127], v[98:99], v[116:117] op_sel_hi:[1,0]
	v_pk_mul_f32 v[146:147], v[96:97], v[116:117] op_sel_hi:[1,0]
	v_pk_mul_f32 v[120:121], v[102:103], v[116:117] op_sel_hi:[1,0]
	v_pk_mul_f32 v[118:119], v[100:101], v[116:117] op_sel_hi:[1,0]
	v_lshlrev_b64 v[122:123], 8, v[122:123]
	v_cvt_pk_bf16_f32 v118, v118, v119
	v_cvt_pk_bf16_f32 v119, v120, v121
	v_cvt_pk_bf16_f32 v120, v146, v147
	v_cvt_pk_bf16_f32 v121, v126, v127
	v_lshl_add_u64 v[122:123], v[138:139], 0, v[122:123]
	s_mov_b64 s[0:1], 0
	global_store_dwordx4 v[122:123], v[118:121], off

; __device__ __forceinline__ u32x4 pack8u(f32x4 a, f32x4 b) { u32x4 w = {cvt_pk_bf16(a[0], a[1]), cvt_pk_bf16(a[2], a[3]), cvt_pk_bf16(b[0], b[1]), cvt_pk_bf16(b[2], b[3])}; return w; }
; __device__ __forceinline__ u32x2 pack4u(f32x4 a) { u32x2 w = {cvt_pk_bf16(a[0], a[1]), cvt_pk_bf16(a[2], a[3])}; return w; }
;     __device__ __forceinline__ void operator()(const AccT& acc, const Unit& u, int wr, int wc, int fr, int fq) const {
;     ...
;                 const int row = u.pm * 256 + ai * 128 + wr * 64 + m * 16 + fr; const int b = row / SEQ, t = row % SEQ;
;                 const f32x4 s0 = *(const f32x4*)(SSQ + (size_t)row * 16 + mode * 8), s1 = *(const f32x4*)(SSQ + (size_t)row * 16 + mode * 8 + 4);
;                 const float ssq = (s0[0] + s0[1]) + (s0[2] + s0[3]) + (s1[0] + s1[1]) + (s1[2] + s1[3]);
;                 float rs = rsqrtf(ssq * (1.0f / 512.0f) + EPS);
;                 if (mode == 0) {
;                     rs *= (0.07216878364870322f * 1.4426950408889634f);
; #pragma unroll
;                     for (int bj = 0; bj < 2; ++bj) {
;                         const int c8 = u.pn * 256 + bj * 128 + wc * 32 + fq * 8; const int head = c8 / DQK, d0 = c8 % DQK;
;                         bf16_t* qp = Q + ((size_t)(b * NH + head) * SEQ + t) * DQK;
;                         const f32x4 v0 = acc[ai][bj][m][0] * rs, v1 = acc[ai][bj][m][1] * rs;
;                         if (d0 < 128) { *(u32x4*)(qp + d0) = pack8u(v0, v1); }
;                         else { const int i0 = 4 * ((d0 - 128) >> 3);
;                             const f32x4 cs = *(const f32x4*)(COS + (size_t)row * 32 + i0), sn = *(const f32x4*)(SIN + (size_t)row * 32 + i0);
;                             const f32x4 o1 = v0 * cs - v1 * sn, o2 = v1 * cs + v0 * sn;
;                             *(u32x2*)(qp + 128 + i0) = pack4u(o1); *(u32x2*)(qp + 160 + i0) = pack4u(o2); }
.LBB0_524:
	v_or_b32_e32 v98, 32, v144
	v_ashrrev_i32_e32 v99, 31, v98
	v_lshlrev_b64 v[102:103], 6, v[98:99]
	v_lshl_add_u64 v[106:107], s[48:49], 0, v[102:103]
	s_waitcnt vmcnt(6)
	v_mov_b32_e32 v102, v192
	v_mov_b32_e32 v103, v193
	v_mov_b32_e32 v104, v194
	v_mov_b32_e32 v105, v195
	s_nop 0
	v_mov_b32_e32 v106, v196
	v_mov_b32_e32 v107, v197
	v_mov_b32_e32 v108, v198
	v_mov_b32_e32 v109, v199
	global_load_dwordx4 v[192:195], v221, s[48:49] offset:2064
	global_load_dwordx4 v[196:199], v221, s[48:49] offset:2048
	v_add_u32_e32 v96, v98, v124
	v_ashrrev_i32_e32 v101, 11, v96
	v_mul_i32_i24_e32 v96, 0x800, v101
	v_sub_u32_e32 v96, v98, v96
	s_mov_b64 s[0:1], -1
	s_nop 0
	v_mov_b32_e32 v110, v107
	v_mov_b32_e32 v111, v108
	v_mov_b32_e32 v107, v109
	v_pk_add_f32 v[106:107], v[110:111], v[106:107]
	v_mov_b32_e32 v108, v104
	v_mov_b32_e32 v109, v102
	v_mov_b32_e32 v102, v105
	v_pk_add_f32 v[102:103], v[108:109], v[102:103]
	v_add_f32_e32 v97, v106, v107
	v_add_f32_e32 v97, v97, v103
	v_add_f32_e32 v97, v102, v97
	v_fmamk_f32 v97, v97, 0x3b000000, v223
	v_cmp_gt_f32_e32 vcc, s60, v97
	v_mul_f32_e32 v100, 0x4b800000, v97
	s_nop 0
	v_cndmask_b32_e32 v97, v97, v100, vcc
	v_rsq_f32_e32 v97, v97
	s_nop 0
	v_mul_f32_e32 v100, 0x45800000, v97
	v_cndmask_b32_e32 v100, v97, v100, vcc
	s_and_b64 vcc, exec, s[42:43]
	v_ashrrev_i32_e32 v97, 31, v96
	s_cbranch_vccnz .LBB0_526
	v_lshl_add_u32 v102, v101, 3, s94
	v_ashrrev_i32_e32 v103, 31, v102
	v_lshlrev_b64 v[102:103], 11, v[102:103]
	v_lshl_add_u64 v[106:107], v[102:103], 0, v[96:97]
	v_pk_mul_f32 v[104:105], v[94:95], v[100:101] op_sel_hi:[1,0]
	v_pk_mul_f32 v[102:103], v[92:93], v[100:101] op_sel_hi:[1,0]
	v_pk_mul_f32 v[108:109], v[90:91], v[100:101] op_sel_hi:[1,0]
	v_pk_mul_f32 v[110:111], v[88:89], v[100:101] op_sel_hi:[1,0]
	v_cvt_pk_bf16_f32 v102, v102, v103
	v_cvt_pk_bf16_f32 v103, v104, v105
	v_cvt_pk_bf16_f32 v105, v108, v109
	v_mad_u64_u32 v[108:109], s[0:1], v106, s33, v[136:137]
	v_cvt_pk_bf16_f32 v104, v110, v111
	v_mad_i32_i24 v109, v107, s33, v109
	global_store_dwordx4 v[108:109], v[102:105], off
	v_pk_mul_f32 v[108:109], v[82:83], v[100:101] op_sel_hi:[1,0]
	v_pk_mul_f32 v[110:111], v[80:81], v[100:101] op_sel_hi:[1,0]
	v_pk_mul_f32 v[104:105], v[86:87], v[100:101] op_sel_hi:[1,0]
	v_pk_mul_f32 v[102:103], v[84:85], v[100:101] op_sel_hi:[1,0]
	v_lshlrev_b64 v[106:107], 8, v[106:107]
	v_cvt_pk_bf16_f32 v102, v102, v103
	v_cvt_pk_bf16_f32 v103, v104, v105
	v_cvt_pk_bf16_f32 v104, v110, v111
	v_cvt_pk_bf16_f32 v105, v108, v109
	v_lshl_add_u64 v[106:107], v[138:139], 0, v[106:107]
	s_mov_b64 s[0:1], 0
	global_store_dwordx4 v[106:107], v[102:105], off

; __device__ __forceinline__ u32x4 pack8u(f32x4 a, f32x4 b) { u32x4 w = {cvt_pk_bf16(a[0], a[1]), cvt_pk_bf16(a[2], a[3]), cvt_pk_bf16(b[0], b[1]), cvt_pk_bf16(b[2], b[3])}; return w; }
; __device__ __forceinline__ u32x2 pack4u(f32x4 a) { u32x2 w = {cvt_pk_bf16(a[0], a[1]), cvt_pk_bf16(a[2], a[3])}; return w; }
;     __device__ __forceinline__ void operator()(const AccT& acc, const Unit& u, int wr, int wc, int fr, int fq) const {
;     ...
;                 const int row = u.pm * 256 + ai * 128 + wr * 64 + m * 16 + fr; const int b = row / SEQ, t = row % SEQ;
;                 const f32x4 s0 = *(const f32x4*)(SSQ + (size_t)row * 16 + mode * 8), s1 = *(const f32x4*)(SSQ + (size_t)row * 16 + mode * 8 + 4);
;                 const float ssq = (s0[0] + s0[1]) + (s0[2] + s0[3]) + (s1[0] + s1[1]) + (s1[2] + s1[3]);
;                 float rs = rsqrtf(ssq * (1.0f / 512.0f) + EPS);
;                 if (mode == 0) {
;                     rs *= (0.07216878364870322f * 1.4426950408889634f);
; #pragma unroll
;                     for (int bj = 0; bj < 2; ++bj) {
;                         const int c8 = u.pn * 256 + bj * 128 + wc * 32 + fq * 8; const int head = c8 / DQK, d0 = c8 % DQK;
;                         bf16_t* qp = Q + ((size_t)(b * NH + head) * SEQ + t) * DQK;
;                         const f32x4 v0 = acc[ai][bj][m][0] * rs, v1 = acc[ai][bj][m][1] * rs;
;                         if (d0 < 128) { *(u32x4*)(qp + d0) = pack8u(v0, v1); }
;                         else { const int i0 = 4 * ((d0 - 128) >> 3);
;                             const f32x4 cs = *(const f32x4*)(COS + (size_t)row * 32 + i0), sn = *(const f32x4*)(SIN + (size_t)row * 32 + i0);
;                             const f32x4 o1 = v0 * cs - v1 * sn, o2 = v1 * cs + v0 * sn;
;                             *(u32x2*)(qp + 128 + i0) = pack4u(o1); *(u32x2*)(qp + 160 + i0) = pack4u(o2); }
;                     }
;                 } else {
;                     const size_t bh = (size_t)(b * NH + u.pn) * SEQ + t; const int d = wc * 32 + fq * 8;
;                     *(u32x4*)(Kb + bh * DQK + d) = pack8u(acc[ai][0][m][0] * rs, acc[ai][0][m][1] * rs);
;                     *(u32x4*)(Vb + bh * 128 + d) = pack8u(acc[ai][1][m][0] * rs, acc[ai][1][m][1] * rs);
.LBB0_536:
	v_or_b32_e32 v82, 48, v144
	v_ashrrev_i32_e32 v83, 31, v82
	v_lshlrev_b64 v[86:87], 6, v[82:83]
	v_lshl_add_u64 v[90:91], s[48:49], 0, v[86:87]
	s_waitcnt vmcnt(6)
	v_mov_b32_e32 v86, v200
	v_mov_b32_e32 v87, v201
	v_mov_b32_e32 v88, v202
	v_mov_b32_e32 v89, v203
	s_nop 0
	v_mov_b32_e32 v90, v204
	v_mov_b32_e32 v91, v205
	v_mov_b32_e32 v92, v206
	v_mov_b32_e32 v93, v207
	global_load_dwordx4 v[200:203], v221, s[48:49] offset:3088
	global_load_dwordx4 v[204:207], v221, s[48:49] offset:3072
	v_add_u32_e32 v80, v82, v124
	v_ashrrev_i32_e32 v85, 11, v80
	v_mul_i32_i24_e32 v80, 0x800, v85
	v_sub_u32_e32 v80, v82, v80
	s_mov_b64 s[0:1], -1
	s_nop 0
	v_mov_b32_e32 v94, v91
	v_mov_b32_e32 v95, v92
	v_mov_b32_e32 v91, v93
	v_pk_add_f32 v[90:91], v[94:95], v[90:91]
	v_mov_b32_e32 v92, v88
	v_mov_b32_e32 v93, v86
	v_mov_b32_e32 v86, v89
	v_pk_add_f32 v[86:87], v[92:93], v[86:87]
	v_add_f32_e32 v81, v90, v91
	v_add_f32_e32 v81, v81, v87
	v_add_f32_e32 v81, v86, v81
	v_fmamk_f32 v81, v81, 0x3b000000, v223
	v_cmp_gt_f32_e32 vcc, s60, v81
	v_mul_f32_e32 v84, 0x4b800000, v81
	s_nop 0
	v_cndmask_b32_e32 v81, v81, v84, vcc
	v_rsq_f32_e32 v81, v81
	s_nop 0
	v_mul_f32_e32 v84, 0x45800000, v81
	v_cndmask_b32_e32 v84, v81, v84, vcc
	s_and_b64 vcc, exec, s[42:43]
	v_ashrrev_i32_e32 v81, 31, v80
	s_cbranch_vccnz .LBB0_538
	v_lshl_add_u32 v86, v85, 3, s94
	v_ashrrev_i32_e32 v87, 31, v86
	v_lshlrev_b64 v[86:87], 11, v[86:87]
	v_lshl_add_u64 v[90:91], v[86:87], 0, v[80:81]
	v_pk_mul_f32 v[88:89], v[78:79], v[84:85] op_sel_hi:[1,0]
	v_pk_mul_f32 v[86:87], v[76:77], v[84:85] op_sel_hi:[1,0]
	v_pk_mul_f32 v[92:93], v[74:75], v[84:85] op_sel_hi:[1,0]
	v_pk_mul_f32 v[94:95], v[72:73], v[84:85] op_sel_hi:[1,0]
	v_cvt_pk_bf16_f32 v86, v86, v87
	v_cvt_pk_bf16_f32 v87, v88, v89
	v_cvt_pk_bf16_f32 v89, v92, v93
	v_mad_u64_u32 v[92:93], s[0:1], v90, s33, v[136:137]
	v_cvt_pk_bf16_f32 v88, v94, v95
	v_mad_i32_i24 v93, v91, s33, v93
	global_store_dwordx4 v[92:93], v[86:89], off
	v_pk_mul_f32 v[92:93], v[66:67], v[84:85] op_sel_hi:[1,0]
	v_pk_mul_f32 v[94:95], v[64:65], v[84:85] op_sel_hi:[1,0]
	v_pk_mul_f32 v[88:89], v[70:71], v[84:85] op_sel_hi:[1,0]
	v_pk_mul_f32 v[86:87], v[68:69], v[84:85] op_sel_hi:[1,0]
	v_lshlrev_b64 v[90:91], 8, v[90:91]
	v_cvt_pk_bf16_f32 v86, v86, v87
	v_cvt_pk_bf16_f32 v87, v88, v89
	v_cvt_pk_bf16_f32 v88, v94, v95
	v_cvt_pk_bf16_f32 v89, v92, v93
	v_lshl_add_u64 v[90:91], v[138:139], 0, v[90:91]
	s_mov_b64 s[0:1], 0
	global_store_dwordx4 v[90:91], v[86:89], off

; __device__ __forceinline__ u32x4 pack8u(f32x4 a, f32x4 b) { u32x4 w = {cvt_pk_bf16(a[0], a[1]), cvt_pk_bf16(a[2], a[3]), cvt_pk_bf16(b[0], b[1]), cvt_pk_bf16(b[2], b[3])}; return w; }
; __device__ __forceinline__ u32x2 pack4u(f32x4 a) { u32x2 w = {cvt_pk_bf16(a[0], a[1]), cvt_pk_bf16(a[2], a[3])}; return w; }
;     __device__ __forceinline__ void operator()(const AccT& acc, const Unit& u, int wr, int wc, int fr, int fq) const {
;     ...
;                 const int row = u.pm * 256 + ai * 128 + wr * 64 + m * 16 + fr; const int b = row / SEQ, t = row % SEQ;
;                 const f32x4 s0 = *(const f32x4*)(SSQ + (size_t)row * 16 + mode * 8), s1 = *(const f32x4*)(SSQ + (size_t)row * 16 + mode * 8 + 4);
;                 const float ssq = (s0[0] + s0[1]) + (s0[2] + s0[3]) + (s1[0] + s1[1]) + (s1[2] + s1[3]);
;                 float rs = rsqrtf(ssq * (1.0f / 512.0f) + EPS);
;                 if (mode == 0) {
;                     rs *= (0.07216878364870322f * 1.4426950408889634f);
; #pragma unroll
;                     for (int bj = 0; bj < 2; ++bj) {
;                         const int c8 = u.pn * 256 + bj * 128 + wc * 32 + fq * 8; const int head = c8 / DQK, d0 = c8 % DQK;
;                         bf16_t* qp = Q + ((size_t)(b * NH + head) * SEQ + t) * DQK;
;                         const f32x4 v0 = acc[ai][bj][m][0] * rs, v1 = acc[ai][bj][m][1] * rs;
;                         if (d0 < 128) { *(u32x4*)(qp + d0) = pack8u(v0, v1); }
;                         else { const int i0 = 4 * ((d0 - 128) >> 3);
;                             const f32x4 cs = *(const f32x4*)(COS + (size_t)row * 32 + i0), sn = *(const f32x4*)(SIN + (size_t)row * 32 + i0);
;                             const f32x4 o1 = v0 * cs - v1 * sn, o2 = v1 * cs + v0 * sn;
;                             *(u32x2*)(qp + 128 + i0) = pack4u(o1); *(u32x2*)(qp + 160 + i0) = pack4u(o2); }
;                     }
;                 } else {
;                     const size_t bh = (size_t)(b * NH + u.pn) * SEQ + t; const int d = wc * 32 + fq * 8;
;                     *(u32x4*)(Kb + bh * DQK + d) = pack8u(acc[ai][0][m][0] * rs, acc[ai][0][m][1] * rs);
;                     *(u32x4*)(Vb + bh * 128 + d) = pack8u(acc[ai][1][m][0] * rs, acc[ai][1][m][1] * rs);
.LBB0_548:
	v_add_u32_e32 v66, 0x80, v144
	v_ashrrev_i32_e32 v67, 31, v66
	v_lshlrev_b64 v[70:71], 6, v[66:67]
	v_lshl_add_u64 v[74:75], s[48:49], 0, v[70:71]
	s_waitcnt vmcnt(6)
	v_mov_b32_e32 v70, v176
	v_mov_b32_e32 v71, v177
	v_mov_b32_e32 v72, v178
	v_mov_b32_e32 v73, v179
	s_nop 0
	v_mov_b32_e32 v74, v180
	v_mov_b32_e32 v75, v181
	v_mov_b32_e32 v76, v182
	v_mov_b32_e32 v77, v183
	v_lshrrev_b32_e32 v64, 21, v67
	v_add_u32_e32 v64, v66, v64
	v_ashrrev_i32_e32 v69, 11, v64
	v_mul_i32_i24_e32 v64, 0x800, v69
	v_sub_u32_e32 v64, v66, v64
	s_mov_b64 s[0:1], -1
	s_nop 0
	v_mov_b32_e32 v78, v75
	v_mov_b32_e32 v79, v76
	v_mov_b32_e32 v75, v77
	v_pk_add_f32 v[74:75], v[78:79], v[74:75]
	v_mov_b32_e32 v76, v72
	v_mov_b32_e32 v77, v70
	v_mov_b32_e32 v70, v73
	v_pk_add_f32 v[70:71], v[76:77], v[70:71]
	v_add_f32_e32 v65, v74, v75
	v_add_f32_e32 v65, v65, v71
	v_add_f32_e32 v65, v70, v65
	v_fmamk_f32 v65, v65, 0x3b000000, v223
	v_cmp_gt_f32_e32 vcc, s60, v65
	v_mul_f32_e32 v68, 0x4b800000, v65
	s_nop 0
	v_cndmask_b32_e32 v65, v65, v68, vcc
	v_rsq_f32_e32 v65, v65
	s_nop 0
	v_mul_f32_e32 v68, 0x45800000, v65
	v_cndmask_b32_e32 v68, v65, v68, vcc
	s_and_b64 vcc, exec, s[42:43]
	v_ashrrev_i32_e32 v65, 31, v64
	s_cbranch_vccnz .LBB0_550
	v_lshl_add_u32 v70, v69, 3, s94
	v_ashrrev_i32_e32 v71, 31, v70
	v_lshlrev_b64 v[70:71], 11, v[70:71]
	v_lshl_add_u64 v[74:75], v[70:71], 0, v[64:65]
	v_pk_mul_f32 v[72:73], v[62:63], v[68:69] op_sel_hi:[1,0]
	v_pk_mul_f32 v[70:71], v[60:61], v[68:69] op_sel_hi:[1,0]
	v_pk_mul_f32 v[76:77], v[58:59], v[68:69] op_sel_hi:[1,0]
	v_pk_mul_f32 v[78:79], v[56:57], v[68:69] op_sel_hi:[1,0]
	v_cvt_pk_bf16_f32 v70, v70, v71
	v_cvt_pk_bf16_f32 v71, v72, v73
	v_cvt_pk_bf16_f32 v73, v76, v77
	v_mad_u64_u32 v[76:77], s[0:1], v74, s33, v[136:137]
	v_cvt_pk_bf16_f32 v72, v78, v79
	v_mad_i32_i24 v77, v75, s33, v77
	global_store_dwordx4 v[76:77], v[70:73], off
	v_pk_mul_f32 v[76:77], v[50:51], v[68:69] op_sel_hi:[1,0]
	v_pk_mul_f32 v[78:79], v[48:49], v[68:69] op_sel_hi:[1,0]
	v_pk_mul_f32 v[72:73], v[54:55], v[68:69] op_sel_hi:[1,0]
	v_pk_mul_f32 v[70:71], v[52:53], v[68:69] op_sel_hi:[1,0]
	v_lshlrev_b64 v[74:75], 8, v[74:75]
	v_cvt_pk_bf16_f32 v70, v70, v71
	v_cvt_pk_bf16_f32 v71, v72, v73
	v_cvt_pk_bf16_f32 v72, v78, v79
	v_cvt_pk_bf16_f32 v73, v76, v77
	v_lshl_add_u64 v[74:75], v[138:139], 0, v[74:75]
	s_mov_b64 s[0:1], 0
	global_store_dwordx4 v[74:75], v[70:73], off

; __device__ __forceinline__ u32x4 pack8u(f32x4 a, f32x4 b) { u32x4 w = {cvt_pk_bf16(a[0], a[1]), cvt_pk_bf16(a[2], a[3]), cvt_pk_bf16(b[0], b[1]), cvt_pk_bf16(b[2], b[3])}; return w; }
; __device__ __forceinline__ u32x2 pack4u(f32x4 a) { u32x2 w = {cvt_pk_bf16(a[0], a[1]), cvt_pk_bf16(a[2], a[3])}; return w; }
;     __device__ __forceinline__ void operator()(const AccT& acc, const Unit& u, int wr, int wc, int fr, int fq) const {
;     ...
;                 const int row = u.pm * 256 + ai * 128 + wr * 64 + m * 16 + fr; const int b = row / SEQ, t = row % SEQ;
;                 const f32x4 s0 = *(const f32x4*)(SSQ + (size_t)row * 16 + mode * 8), s1 = *(const f32x4*)(SSQ + (size_t)row * 16 + mode * 8 + 4);
;                 const float ssq = (s0[0] + s0[1]) + (s0[2] + s0[3]) + (s1[0] + s1[1]) + (s1[2] + s1[3]);
;                 float rs = rsqrtf(ssq * (1.0f / 512.0f) + EPS);
;                 if (mode == 0) {
;                     rs *= (0.07216878364870322f * 1.4426950408889634f);
; #pragma unroll
;                     for (int bj = 0; bj < 2; ++bj) {
;                         const int c8 = u.pn * 256 + bj * 128 + wc * 32 + fq * 8; const int head = c8 / DQK, d0 = c8 % DQK;
;                         bf16_t* qp = Q + ((size_t)(b * NH + head) * SEQ + t) * DQK;
;                         const f32x4 v0 = acc[ai][bj][m][0] * rs, v1 = acc[ai][bj][m][1] * rs;
;                         if (d0 < 128) { *(u32x4*)(qp + d0) = pack8u(v0, v1); }
;                         else { const int i0 = 4 * ((d0 - 128) >> 3);
;                             const f32x4 cs = *(const f32x4*)(COS + (size_t)row * 32 + i0), sn = *(const f32x4*)(SIN + (size_t)row * 32 + i0);
;                             const f32x4 o1 = v0 * cs - v1 * sn, o2 = v1 * cs + v0 * sn;
;                             *(u32x2*)(qp + 128 + i0) = pack4u(o1); *(u32x2*)(qp + 160 + i0) = pack4u(o2); }
;                     }
;                 } else {
;                     const size_t bh = (size_t)(b * NH + u.pn) * SEQ + t; const int d = wc * 32 + fq * 8;
;                     *(u32x4*)(Kb + bh * DQK + d) = pack8u(acc[ai][0][m][0] * rs, acc[ai][0][m][1] * rs);
;                     *(u32x4*)(Vb + bh * 128 + d) = pack8u(acc[ai][1][m][0] * rs, acc[ai][1][m][1] * rs);
.LBB0_560:
	v_add_u32_e32 v50, 0x90, v144
	v_ashrrev_i32_e32 v51, 31, v50
	v_lshlrev_b64 v[54:55], 6, v[50:51]
	v_lshl_add_u64 v[58:59], s[48:49], 0, v[54:55]
	s_waitcnt vmcnt(4)
	v_mov_b32_e32 v54, v184
	v_mov_b32_e32 v55, v185
	v_mov_b32_e32 v56, v186
	v_mov_b32_e32 v57, v187
	s_nop 0
	v_mov_b32_e32 v58, v188
	v_mov_b32_e32 v59, v189
	v_mov_b32_e32 v60, v190
	v_mov_b32_e32 v61, v191
	v_lshrrev_b32_e32 v48, 21, v51
	v_add_u32_e32 v48, v50, v48
	v_ashrrev_i32_e32 v53, 11, v48
	v_mul_i32_i24_e32 v48, 0x800, v53
	v_sub_u32_e32 v48, v50, v48
	s_mov_b64 s[0:1], -1
	s_nop 0
	v_mov_b32_e32 v62, v59
	v_mov_b32_e32 v63, v60
	v_mov_b32_e32 v59, v61
	v_pk_add_f32 v[58:59], v[62:63], v[58:59]
	v_mov_b32_e32 v60, v56
	v_mov_b32_e32 v61, v54
	v_mov_b32_e32 v54, v57
	v_pk_add_f32 v[54:55], v[60:61], v[54:55]
	v_add_f32_e32 v49, v58, v59
	v_add_f32_e32 v49, v49, v55
	v_add_f32_e32 v49, v54, v49
	v_fmamk_f32 v49, v49, 0x3b000000, v223
	v_cmp_gt_f32_e32 vcc, s60, v49
	v_mul_f32_e32 v52, 0x4b800000, v49
	s_nop 0
	v_cndmask_b32_e32 v49, v49, v52, vcc
	v_rsq_f32_e32 v49, v49
	s_nop 0
	v_mul_f32_e32 v52, 0x45800000, v49
	v_cndmask_b32_e32 v52, v49, v52, vcc
	s_and_b64 vcc, exec, s[42:43]
	v_ashrrev_i32_e32 v49, 31, v48
	s_cbranch_vccnz .LBB0_562
	v_lshl_add_u32 v54, v53, 3, s94
	v_ashrrev_i32_e32 v55, 31, v54
	v_lshlrev_b64 v[54:55], 11, v[54:55]
	v_lshl_add_u64 v[58:59], v[54:55], 0, v[48:49]
	v_pk_mul_f32 v[56:57], v[46:47], v[52:53] op_sel_hi:[1,0]
	v_pk_mul_f32 v[54:55], v[44:45], v[52:53] op_sel_hi:[1,0]
	v_pk_mul_f32 v[60:61], v[42:43], v[52:53] op_sel_hi:[1,0]
	v_pk_mul_f32 v[62:63], v[40:41], v[52:53] op_sel_hi:[1,0]
	v_cvt_pk_bf16_f32 v54, v54, v55
	v_cvt_pk_bf16_f32 v55, v56, v57
	v_cvt_pk_bf16_f32 v57, v60, v61
	v_mad_u64_u32 v[60:61], s[0:1], v58, s33, v[136:137]
	v_cvt_pk_bf16_f32 v56, v62, v63
	v_mad_i32_i24 v61, v59, s33, v61
	global_store_dwordx4 v[60:61], v[54:57], off
	v_pk_mul_f32 v[60:61], v[34:35], v[52:53] op_sel_hi:[1,0]
	v_pk_mul_f32 v[62:63], v[32:33], v[52:53] op_sel_hi:[1,0]
	v_pk_mul_f32 v[56:57], v[38:39], v[52:53] op_sel_hi:[1,0]
	v_pk_mul_f32 v[54:55], v[36:37], v[52:53] op_sel_hi:[1,0]
	v_lshlrev_b64 v[58:59], 8, v[58:59]
	v_cvt_pk_bf16_f32 v54, v54, v55
	v_cvt_pk_bf16_f32 v55, v56, v57
	v_cvt_pk_bf16_f32 v56, v62, v63
	v_cvt_pk_bf16_f32 v57, v60, v61
	v_lshl_add_u64 v[58:59], v[138:139], 0, v[58:59]
	s_mov_b64 s[0:1], 0
	global_store_dwordx4 v[58:59], v[54:57], off

; __device__ __forceinline__ u32x4 pack8u(f32x4 a, f32x4 b) { u32x4 w = {cvt_pk_bf16(a[0], a[1]), cvt_pk_bf16(a[2], a[3]), cvt_pk_bf16(b[0], b[1]), cvt_pk_bf16(b[2], b[3])}; return w; }
; __device__ __forceinline__ u32x2 pack4u(f32x4 a) { u32x2 w = {cvt_pk_bf16(a[0], a[1]), cvt_pk_bf16(a[2], a[3])}; return w; }
;     __device__ __forceinline__ void operator()(const AccT& acc, const Unit& u, int wr, int wc, int fr, int fq) const {
;     ...
;                 const int row = u.pm * 256 + ai * 128 + wr * 64 + m * 16 + fr; const int b = row / SEQ, t = row % SEQ;
;                 const f32x4 s0 = *(const f32x4*)(SSQ + (size_t)row * 16 + mode * 8), s1 = *(const f32x4*)(SSQ + (size_t)row * 16 + mode * 8 + 4);
;                 const float ssq = (s0[0] + s0[1]) + (s0[2] + s0[3]) + (s1[0] + s1[1]) + (s1[2] + s1[3]);
;                 float rs = rsqrtf(ssq * (1.0f / 512.0f) + EPS);
;                 if (mode == 0) {
;                     rs *= (0.07216878364870322f * 1.4426950408889634f);
; #pragma unroll
;                     for (int bj = 0; bj < 2; ++bj) {
;                         const int c8 = u.pn * 256 + bj * 128 + wc * 32 + fq * 8; const int head = c8 / DQK, d0 = c8 % DQK;
;                         bf16_t* qp = Q + ((size_t)(b * NH + head) * SEQ + t) * DQK;
;                         const f32x4 v0 = acc[ai][bj][m][0] * rs, v1 = acc[ai][bj][m][1] * rs;
;                         if (d0 < 128) { *(u32x4*)(qp + d0) = pack8u(v0, v1); }
;                         else { const int i0 = 4 * ((d0 - 128) >> 3);
;                             const f32x4 cs = *(const f32x4*)(COS + (size_t)row * 32 + i0), sn = *(const f32x4*)(SIN + (size_t)row * 32 + i0);
;                             const f32x4 o1 = v0 * cs - v1 * sn, o2 = v1 * cs + v0 * sn;
;                             *(u32x2*)(qp + 128 + i0) = pack4u(o1); *(u32x2*)(qp + 160 + i0) = pack4u(o2); }
;                     }
;                 } else {
;                     const size_t bh = (size_t)(b * NH + u.pn) * SEQ + t; const int d = wc * 32 + fq * 8;
;                     *(u32x4*)(Kb + bh * DQK + d) = pack8u(acc[ai][0][m][0] * rs, acc[ai][0][m][1] * rs);
;                     *(u32x4*)(Vb + bh * 128 + d) = pack8u(acc[ai][1][m][0] * rs, acc[ai][1][m][1] * rs);
.LBB0_572:
	v_add_u32_e32 v34, 0xa0, v144
	v_ashrrev_i32_e32 v35, 31, v34
	v_lshlrev_b64 v[38:39], 6, v[34:35]
	v_lshl_add_u64 v[42:43], s[48:49], 0, v[38:39]
	s_waitcnt vmcnt(2)
	v_mov_b32_e32 v38, v192
	v_mov_b32_e32 v39, v193
	v_mov_b32_e32 v40, v194
	v_mov_b32_e32 v41, v195
	s_nop 0
	v_mov_b32_e32 v42, v196
	v_mov_b32_e32 v43, v197
	v_mov_b32_e32 v44, v198
	v_mov_b32_e32 v45, v199
	v_lshrrev_b32_e32 v32, 21, v35
	v_add_u32_e32 v32, v34, v32
	v_ashrrev_i32_e32 v37, 11, v32
	v_mul_i32_i24_e32 v32, 0x800, v37
	v_sub_u32_e32 v32, v34, v32
	s_mov_b64 s[0:1], -1
	s_nop 0
	v_mov_b32_e32 v46, v43
	v_mov_b32_e32 v47, v44
	v_mov_b32_e32 v43, v45
	v_pk_add_f32 v[42:43], v[46:47], v[42:43]
	v_mov_b32_e32 v44, v40
	v_mov_b32_e32 v45, v38
	v_mov_b32_e32 v38, v41
	v_pk_add_f32 v[38:39], v[44:45], v[38:39]
	v_add_f32_e32 v33, v42, v43
	v_add_f32_e32 v33, v33, v39
	v_add_f32_e32 v33, v38, v33
	v_fmamk_f32 v33, v33, 0x3b000000, v223
	v_cmp_gt_f32_e32 vcc, s60, v33
	v_mul_f32_e32 v36, 0x4b800000, v33
	s_nop 0
	v_cndmask_b32_e32 v33, v33, v36, vcc
	v_rsq_f32_e32 v33, v33
	s_nop 0
	v_mul_f32_e32 v36, 0x45800000, v33
	v_cndmask_b32_e32 v36, v33, v36, vcc
	s_and_b64 vcc, exec, s[42:43]
	v_ashrrev_i32_e32 v33, 31, v32
	s_cbranch_vccnz .LBB0_574
	v_lshl_add_u32 v38, v37, 3, s94
	v_ashrrev_i32_e32 v39, 31, v38
	v_lshlrev_b64 v[38:39], 11, v[38:39]
	v_lshl_add_u64 v[42:43], v[38:39], 0, v[32:33]
	v_pk_mul_f32 v[40:41], v[30:31], v[36:37] op_sel_hi:[1,0]
	v_pk_mul_f32 v[38:39], v[28:29], v[36:37] op_sel_hi:[1,0]
	v_pk_mul_f32 v[44:45], v[26:27], v[36:37] op_sel_hi:[1,0]
	v_pk_mul_f32 v[46:47], v[24:25], v[36:37] op_sel_hi:[1,0]
	v_cvt_pk_bf16_f32 v38, v38, v39
	v_cvt_pk_bf16_f32 v39, v40, v41
	v_cvt_pk_bf16_f32 v41, v44, v45
	v_mad_u64_u32 v[44:45], s[0:1], v42, s33, v[136:137]
	v_cvt_pk_bf16_f32 v40, v46, v47
	v_mad_i32_i24 v45, v43, s33, v45
	global_store_dwordx4 v[44:45], v[38:41], off
	v_pk_mul_f32 v[44:45], v[18:19], v[36:37] op_sel_hi:[1,0]
	v_pk_mul_f32 v[46:47], v[16:17], v[36:37] op_sel_hi:[1,0]
	v_pk_mul_f32 v[40:41], v[22:23], v[36:37] op_sel_hi:[1,0]
	v_pk_mul_f32 v[38:39], v[20:21], v[36:37] op_sel_hi:[1,0]
	v_lshlrev_b64 v[42:43], 8, v[42:43]
	v_cvt_pk_bf16_f32 v38, v38, v39
	v_cvt_pk_bf16_f32 v39, v40, v41
	v_cvt_pk_bf16_f32 v40, v46, v47
	v_cvt_pk_bf16_f32 v41, v44, v45
	v_lshl_add_u64 v[42:43], v[138:139], 0, v[42:43]
	s_mov_b64 s[0:1], 0
	global_store_dwordx4 v[42:43], v[38:41], off

; __device__ __forceinline__ u32x4 pack8u(f32x4 a, f32x4 b) { u32x4 w = {cvt_pk_bf16(a[0], a[1]), cvt_pk_bf16(a[2], a[3]), cvt_pk_bf16(b[0], b[1]), cvt_pk_bf16(b[2], b[3])}; return w; }
; __device__ __forceinline__ u32x2 pack4u(f32x4 a) { u32x2 w = {cvt_pk_bf16(a[0], a[1]), cvt_pk_bf16(a[2], a[3])}; return w; }
;     __device__ __forceinline__ void operator()(const AccT& acc, const Unit& u, int wr, int wc, int fr, int fq) const {
;     ...
;                 const int row = u.pm * 256 + ai * 128 + wr * 64 + m * 16 + fr; const int b = row / SEQ, t = row % SEQ;
;                 const f32x4 s0 = *(const f32x4*)(SSQ + (size_t)row * 16 + mode * 8), s1 = *(const f32x4*)(SSQ + (size_t)row * 16 + mode * 8 + 4);
;                 const float ssq = (s0[0] + s0[1]) + (s0[2] + s0[3]) + (s1[0] + s1[1]) + (s1[2] + s1[3]);
;                 float rs = rsqrtf(ssq * (1.0f / 512.0f) + EPS);
;                 if (mode == 0) {
;                     rs *= (0.07216878364870322f * 1.4426950408889634f);
; #pragma unroll
;                     for (int bj = 0; bj < 2; ++bj) {
;                         const int c8 = u.pn * 256 + bj * 128 + wc * 32 + fq * 8; const int head = c8 / DQK, d0 = c8 % DQK;
;                         bf16_t* qp = Q + ((size_t)(b * NH + head) * SEQ + t) * DQK;
;                         const f32x4 v0 = acc[ai][bj][m][0] * rs, v1 = acc[ai][bj][m][1] * rs;
;                         if (d0 < 128) { *(u32x4*)(qp + d0) = pack8u(v0, v1); }
;                         else { const int i0 = 4 * ((d0 - 128) >> 3);
;                             const f32x4 cs = *(const f32x4*)(COS + (size_t)row * 32 + i0), sn = *(const f32x4*)(SIN + (size_t)row * 32 + i0);
;                             const f32x4 o1 = v0 * cs - v1 * sn, o2 = v1 * cs + v0 * sn;
;                             *(u32x2*)(qp + 128 + i0) = pack4u(o1); *(u32x2*)(qp + 160 + i0) = pack4u(o2); }
;                     }
;                 } else {
;                     const size_t bh = (size_t)(b * NH + u.pn) * SEQ + t; const int d = wc * 32 + fq * 8;
;                     *(u32x4*)(Kb + bh * DQK + d) = pack8u(acc[ai][0][m][0] * rs, acc[ai][0][m][1] * rs);
;                     *(u32x4*)(Vb + bh * 128 + d) = pack8u(acc[ai][1][m][0] * rs, acc[ai][1][m][1] * rs);
.LBB0_584:
	s_nop 0
	v_add_u32_e32 v20, 0xb0, v144
	v_ashrrev_i32_e32 v21, 31, v20
	v_lshlrev_b64 v[16:17], 6, v[20:21]
	v_lshl_add_u64 v[22:23], s[48:49], 0, v[16:17]
	s_waitcnt vmcnt(0)
	v_mov_b32_e32 v16, v204
	v_mov_b32_e32 v17, v205
	v_mov_b32_e32 v18, v206
	v_mov_b32_e32 v19, v207
	s_nop 0
	v_mov_b32_e32 v22, v200
	v_mov_b32_e32 v23, v201
	v_mov_b32_e32 v24, v202
	v_mov_b32_e32 v25, v203
	v_lshrrev_b32_e32 v26, 21, v21
	v_add_u32_e32 v28, v20, v26
	s_mov_b64 s[26:27], -1
	s_and_b64 vcc, exec, s[42:43]
	s_nop 0
	v_mov_b32_e32 v26, v17
	v_mov_b32_e32 v27, v18
	v_mov_b32_e32 v17, v19
	v_mov_b32_e32 v18, v24
	v_mov_b32_e32 v19, v22
	v_mov_b32_e32 v22, v25
	v_pk_add_f32 v[16:17], v[26:27], v[16:17]
	v_pk_add_f32 v[18:19], v[18:19], v[22:23]
	v_add_f32_e32 v16, v16, v17
	v_add_f32_e32 v16, v16, v19
	v_add_f32_e32 v16, v18, v16
	v_fmamk_f32 v16, v16, 0x3b000000, v223
	v_mul_f32_e32 v17, 0x4b800000, v16
	v_cmp_gt_f32_e64 s[0:1], s60, v16
	v_ashrrev_i32_e32 v19, 11, v28
	s_nop 0
	v_cndmask_b32_e64 v16, v16, v17, s[0:1]
	v_rsq_f32_e32 v17, v16
	v_mul_i32_i24_e32 v16, 0x800, v19
	v_sub_u32_e32 v16, v20, v16
	v_mul_f32_e32 v18, 0x45800000, v17
	v_cndmask_b32_e64 v18, v17, v18, s[0:1]
	v_ashrrev_i32_e32 v17, 31, v16
	s_cbranch_vccnz .LBB0_586
	v_lshl_add_u32 v22, v19, 3, s94
	v_ashrrev_i32_e32 v23, 31, v22
	v_lshlrev_b64 v[22:23], 11, v[22:23]
	v_lshl_add_u64 v[26:27], v[22:23], 0, v[16:17]
	v_pk_mul_f32 v[24:25], v[14:15], v[18:19] op_sel_hi:[1,0]
	v_pk_mul_f32 v[22:23], v[12:13], v[18:19] op_sel_hi:[1,0]
	v_pk_mul_f32 v[28:29], v[10:11], v[18:19] op_sel_hi:[1,0]
	v_pk_mul_f32 v[30:31], v[8:9], v[18:19] op_sel_hi:[1,0]
	v_cvt_pk_bf16_f32 v22, v22, v23
	v_cvt_pk_bf16_f32 v23, v24, v25
	v_cvt_pk_bf16_f32 v25, v28, v29
	v_mad_u64_u32 v[28:29], s[0:1], v26, s33, v[136:137]
	v_cvt_pk_bf16_f32 v24, v30, v31
	v_mad_i32_i24 v29, v27, s33, v29
	global_store_dwordx4 v[28:29], v[22:25], off
	v_pk_mul_f32 v[28:29], v[2:3], v[18:19] op_sel_hi:[1,0]
	v_pk_mul_f32 v[30:31], v[0:1], v[18:19] op_sel_hi:[1,0]
	v_pk_mul_f32 v[24:25], v[6:7], v[18:19] op_sel_hi:[1,0]
	v_pk_mul_f32 v[22:23], v[4:5], v[18:19] op_sel_hi:[1,0]
	v_lshlrev_b64 v[26:27], 8, v[26:27]
	v_cvt_pk_bf16_f32 v22, v22, v23
	v_cvt_pk_bf16_f32 v23, v24, v25
	v_cvt_pk_bf16_f32 v24, v30, v31
	v_cvt_pk_bf16_f32 v25, v28, v29
	v_lshl_add_u64 v[26:27], v[138:139], 0, v[26:27]
	s_mov_b64 s[26:27], 0
	global_store_dwordx4 v[26:27], v[22:25], off
